# PEER dequant scales interleaved {dqu,dqv}: one 8-byte gather per expert in the u-pass (2 gathers per token instead of 4); on top of the nt cache hints
# speedup vs baseline: 1.0042x; 1.0042x over previous
; #define GAS __attribute__((address_space(1)))
; __device__ __forceinline__ void phase_convert_tables(const float* U, const float* V, unsigned char* ws) {
;     const int tid = threadIdx.x, lane = tid & 63, wave = __builtin_amdgcn_readfirstlane(tid >> 6);
;     const int gw = blockIdx.x * NWAVES + wave, NGW = gridDim.x * NWAVES;
;     f32x4 nv[4];
;     { const int row0 = gw; if (row0 < 4 * NEXP) { const bool isv0 = row0 >= 2 * NEXP; const int r0 = row0 & (2 * NEXP - 1); const GAS f32x4* s0 = (const GAS f32x4*)((isv0 ? V : U) + (size_t)r0 * D) + 4 * lane;
; #pragma unroll
;         for (int j = 0; j < 4; ++j) nv[j] = s0[j]; } }
;     for (int row = gw; row < 4 * NEXP; row += NGW) {
;         const bool isv = row >= 2 * NEXP; const int r = row & (2 * NEXP - 1);
;         const GAS f32x4* src = (const GAS f32x4*)((isv ? V : U) + (size_t)r * D) + 4 * lane; const int sstep = 1;
;         f32x4 v[4]; float m = 0.f; (void)src; (void)sstep;
; #pragma unroll
;         for (int j = 0; j < 4; ++j) { v[j] = nv[j]; m = fmaxf(fmaxf(m, fmaxf(fabsf(v[j].x), fabsf(v[j].y))), fmaxf(fabsf(v[j].z), fabsf(v[j].w))); }
;         { const int rown = row + NGW; if (rown < 4 * NEXP) { const bool isvn = rown >= 2 * NEXP; const int rn = rown & (2 * NEXP - 1); const GAS f32x4* sn = (const GAS f32x4*)((isvn ? V : U) + (size_t)rn * D) + 4 * lane;
; #pragma unroll
;             for (int j = 0; j < 4; ++j) nv[j] = sn[j]; } }
; #pragma unroll
;         for (int o = 1; o < 64; o <<= 1) m = fmaxf(m, __shfl_xor(m, o));
;         m = fmaxf(m, 1e-30f);
;         const float sc = 7.f / m;
.LBB0_78:
	s_or_b64 exec, exec, s[4:5]
	s_andn2_b64 vcc, exec, s[12:13]
	s_cbranch_vccnz .LBB0_86
	v_readfirstlane_b32 s0, v0
	s_lshr_b32 s0, s0, 6
	s_add_i32 s2, s0, s31
	s_cmp_gt_i32 s2, 0xffff
	s_cbranch_scc1 .LBB0_86
	s_cmpk_gt_i32 s2, 0x7fff
	s_cselect_b32 s1, s55, s53
	s_cselect_b32 s3, s54, s52
	s_lshl_b32 s4, s2, 12
	s_and_b32 s4, s4, 0x7fff000
	s_add_u32 s4, s3, s4
	s_addc_u32 s5, s1, 0
	v_lshlrev_b32_e32 v1, 6, v34
	global_load_dwordx4 v[14:17], v1, s[4:5] nt
	global_load_dwordx4 v[10:13], v1, s[4:5] offset:16 nt
	global_load_dwordx4 v[6:9], v1, s[4:5] offset:32 nt
	global_load_dwordx4 v[2:5], v1, s[4:5] offset:48 nt
	v_mbcnt_lo_u32_b32 v1, -1, 0
	v_mbcnt_hi_u32_b32 v19, -1, v1
	v_and_b32_e32 v1, 64, v19
	v_add_u32_e32 v20, 64, v1
	v_xor_b32_e32 v1, 1, v19
	v_cmp_lt_i32_e32 vcc, v1, v20
	v_xor_b32_e32 v21, 2, v19
	s_add_i32 s0, s0, s30
	v_cndmask_b32_e32 v1, v19, v1, vcc
	v_cmp_lt_i32_e32 vcc, v21, v20
	s_add_i32 s0, s0, s31
	v_lshlrev_b32_e32 v18, 2, v34
	v_cndmask_b32_e32 v21, v19, v21, vcc
	v_lshlrev_b32_e32 v35, 2, v21
	v_xor_b32_e32 v21, 4, v19
	v_cmp_lt_i32_e32 vcc, v21, v20
	s_lshl_b32 s8, s0, 10
	v_readlane_b32 s0, v255, 9
	v_cndmask_b32_e32 v21, v19, v21, vcc
	v_lshlrev_b32_e32 v36, 2, v21
	v_xor_b32_e32 v21, 8, v19
	v_cmp_lt_i32_e32 vcc, v21, v20
	v_cmp_eq_u32_e64 s[4:5], 0, v34
	v_lshlrev_b32_e32 v1, 2, v1
	v_cndmask_b32_e32 v21, v19, v21, vcc
	v_lshlrev_b32_e32 v37, 2, v21
	v_xor_b32_e32 v21, 16, v19
	v_cmp_lt_i32_e32 vcc, v21, v20
	s_lshl_b32 s9, s0, 13
	v_lshlrev_b32_e32 v40, 4, v18
	v_cndmask_b32_e32 v21, v19, v21, vcc
	v_lshlrev_b32_e32 v38, 2, v21
	v_xor_b32_e32 v21, 32, v19
	v_cmp_lt_i32_e32 vcc, v21, v20
	s_mov_b32 s12, 0xda24260
	s_mov_b32 s13, 0x40e00000
	v_cndmask_b32_e32 v19, v19, v21, vcc
	v_lshlrev_b32_e32 v39, 2, v19
	s_mov_b32 s14, 0xc0c00000
	s_brev_b32 s15, 32
	v_lshlrev_b32_e32 v34, 3, v34
	s_mov_b32 s16, 0x1d00004
	v_mov_b32_e32 v41, 0x40c00000
	v_readlane_b32 s1, v255, 10
	s_branch .LBB0_82

; #define GAS __attribute__((address_space(1)))
; #define Q4(x) fminf(fmaxf((x) * sc, -6.f), 6.f)
; #define Q4(x) fminf(fmaxf((x) * sc, -6.f), 6.f)
; __device__ __forceinline__ void phase_convert_tables(const float* U, const float* V, unsigned char* ws) {
;     ...
;     for (int row = gw; row < 4 * NEXP; row += NGW) {
;         const bool isv = row >= 2 * NEXP; const int r = row & (2 * NEXP - 1);
;         const GAS f32x4* src = (const GAS f32x4*)((isv ? V : U) + (size_t)r * D) + 4 * lane; const int sstep = 1;
;         f32x4 v[4]; float m = 0.f; (void)src; (void)sstep;
; #pragma unroll
;         for (int j = 0; j < 4; ++j) { v[j] = nv[j]; m = fmaxf(fmaxf(m, fmaxf(fabsf(v[j].x), fabsf(v[j].y))), fmaxf(fabsf(v[j].z), fabsf(v[j].w))); }
;         { const int rown = row + NGW; if (rown < 4 * NEXP) { const bool isvn = rown >= 2 * NEXP; const int rn = rown & (2 * NEXP - 1); const GAS f32x4* sn = (const GAS f32x4*)((isvn ? V : U) + (size_t)rn * D) + 4 * lane;
; #pragma unroll
;             for (int j = 0; j < 4; ++j) nv[j] = sn[j]; } }
; #pragma unroll
;         for (int o = 1; o < 64; o <<= 1) m = fmaxf(m, __shfl_xor(m, o));
;         m = fmaxf(m, 1e-30f);
;         const float sc = 7.f / m;
;         unsigned w0 = 0u, w1 = 0u;
;     ...
;         w0 = __builtin_amdgcn_cvt_scalef32_pk_fp4_f32(w0, Q4(v[0].x), Q4(v[0].y), 1.0f, 0); w0 = __builtin_amdgcn_cvt_scalef32_pk_fp4_f32(w0, Q4(v[0].z), Q4(v[0].w), 1.0f, 1);
;         w0 = __builtin_amdgcn_cvt_scalef32_pk_fp4_f32(w0, Q4(v[1].x), Q4(v[1].y), 1.0f, 2); w0 = __builtin_amdgcn_cvt_scalef32_pk_fp4_f32(w0, Q4(v[1].z), Q4(v[1].w), 1.0f, 3);
;         w1 = __builtin_amdgcn_cvt_scalef32_pk_fp4_f32(w1, Q4(v[2].x), Q4(v[2].y), 1.0f, 0); w1 = __builtin_amdgcn_cvt_scalef32_pk_fp4_f32(w1, Q4(v[2].z), Q4(v[2].w), 1.0f, 1);
;         w1 = __builtin_amdgcn_cvt_scalef32_pk_fp4_f32(w1, Q4(v[3].x), Q4(v[3].y), 1.0f, 2); w1 = __builtin_amdgcn_cvt_scalef32_pk_fp4_f32(w1, Q4(v[3].z), Q4(v[3].w), 1.0f, 3);
;     ...
;         *((GAS v2u*)(ws + (isv ? WS_V8 : WS_U8) + (size_t)r * 512) + lane) = (v2u){w0, w1};
;         if (lane == 0) ((float*)(ws + (isv ? WS_DQV : WS_DQU)))[r] = m * (1.f / 7.f);
.LBB0_84:
	v_max_f32_e64 v42, |v15|, |v15|
	v_max_f32_e64 v43, |v14|, |v14|
	v_max_f32_e32 v42, v43, v42
	v_max_f32_e64 v43, |v17|, |v17|
	v_max_f32_e64 v44, |v16|, |v16|
	v_max_f32_e32 v43, v44, v43
	v_max3_f32 v42, v42, 0, v43
	v_max_f32_e64 v43, |v11|, |v11|
	v_max_f32_e64 v44, |v10|, |v10|
	v_max_f32_e32 v43, v44, v43
	v_max_f32_e64 v44, |v13|, |v13|
	v_max_f32_e64 v45, |v12|, |v12|
	v_max_f32_e32 v44, v45, v44
	v_max3_f32 v42, v42, v43, v44
	v_max_f32_e64 v43, |v7|, |v7|
	v_max_f32_e64 v44, |v6|, |v6|
	v_max_f32_e32 v43, v44, v43
	v_max_f32_e64 v44, |v9|, |v9|
	v_max_f32_e64 v45, |v8|, |v8|
	v_max_f32_e32 v44, v45, v44
	v_max3_f32 v42, v42, v43, v44
	v_max_f32_e64 v43, |v3|, |v3|
	v_max_f32_e64 v44, |v2|, |v2|
	v_max_f32_e32 v43, v44, v43
	v_max_f32_e64 v44, |v5|, |v5|
	v_max_f32_e64 v45, |v4|, |v4|
	v_max_f32_e32 v44, v45, v44
	v_max3_f32 v42, v42, v43, v44
	ds_bpermute_b32 v43, v1, v42
	s_and_b32 s18, s2, 0x7fff
	s_cmpk_gt_i32 s2, 0x7fff
	s_cselect_b64 s[2:3], -1, 0
	s_and_b64 s[6:7], s[2:3], exec
	s_waitcnt lgkmcnt(0)
	v_max_f32_e32 v43, v43, v43
	v_max_f32_e32 v42, v42, v43
	ds_bpermute_b32 v43, v35, v42
	s_waitcnt lgkmcnt(0)
	v_max_f32_e32 v43, v43, v43
	v_max_f32_e32 v42, v42, v43
	ds_bpermute_b32 v43, v36, v42
	s_waitcnt lgkmcnt(0)
	v_max_f32_e32 v43, v43, v43
	v_max_f32_e32 v42, v42, v43
	ds_bpermute_b32 v43, v37, v42
	s_waitcnt lgkmcnt(0)
	v_max_f32_e32 v43, v43, v43
	v_max_f32_e32 v42, v42, v43
	ds_bpermute_b32 v43, v38, v42
	s_waitcnt lgkmcnt(0)
	v_max_f32_e32 v43, v43, v43
	v_max_f32_e32 v42, v42, v43
	ds_bpermute_b32 v43, v39, v42
	s_waitcnt lgkmcnt(0)
	v_max3_f32 v42, v42, v43, s12
	v_div_scale_f32 v43, s[6:7], v42, v42, s13
	v_rcp_f32_e32 v44, v43
	s_cselect_b32 s6, s15, 0x2000000
	s_add_u32 s6, s82, s6
	s_addc_u32 s7, s83, 0
	v_fma_f32 v45, -v43, v44, 1.0
	v_fmac_f32_e32 v44, v45, v44
	v_div_scale_f32 v45, vcc, s13, v42, s13
	v_mul_f32_e32 v46, v45, v44
	v_fma_f32 v47, -v43, v46, v45
	v_fmac_f32_e32 v46, v47, v44
	v_fma_f32 v43, -v43, v46, v45
	v_div_fmas_f32 v43, v43, v44, v46
	v_div_fixup_f32 v43, v43, v42, s13
	v_mul_f32_e32 v14, v14, v43
	v_med3_f32 v44, v14, s14, v41
	v_mul_f32_e32 v14, v15, v43
	v_med3_f32 v15, v14, s14, v41
	v_mov_b32_e32 v14, 0
	v_cvt_scalef32_pk_fp4_f32 v14, v44, v15, 1.0
	v_mul_f32_e32 v15, v16, v43
	v_mul_f32_e32 v16, v17, v43
	v_med3_f32 v15, v15, s14, v41
	v_med3_f32 v16, v16, s14, v41
	v_mul_f32_e32 v6, v6, v43
	v_mul_f32_e32 v7, v7, v43
	v_cvt_scalef32_pk_fp4_f32 v14, v15, v16, 1.0 op_sel:[0,0,1,0]
	v_med3_f32 v6, v6, s14, v41
	v_med3_f32 v7, v7, s14, v41
	v_mov_b32_e32 v15, 0
	v_cvt_scalef32_pk_fp4_f32 v15, v6, v7, 1.0
	v_mul_f32_e32 v6, v8, v43
	v_mul_f32_e32 v7, v9, v43
	v_mul_f32_e32 v10, v10, v43
	v_mul_f32_e32 v11, v11, v43
	v_med3_f32 v6, v6, s14, v41
	v_med3_f32 v7, v7, s14, v41
	v_mul_f32_e32 v2, v2, v43
	v_mul_f32_e32 v3, v3, v43
	v_med3_f32 v10, v10, s14, v41
	v_med3_f32 v11, v11, s14, v41
	v_cvt_scalef32_pk_fp4_f32 v15, v6, v7, 1.0 op_sel:[0,0,1,0]
	v_med3_f32 v2, v2, s14, v41
	v_med3_f32 v3, v3, s14, v41
	v_cvt_scalef32_pk_fp4_f32 v14, v10, v11, 1.0 op_sel:[0,0,0,1]
	v_mul_f32_e32 v10, v12, v43
	v_mul_f32_e32 v11, v13, v43
	v_cvt_scalef32_pk_fp4_f32 v15, v2, v3, 1.0 op_sel:[0,0,0,1]
	v_mul_f32_e32 v2, v4, v43
	v_mul_f32_e32 v3, v5, v43
	s_lshl_b32 s19, s18, 9
	v_med3_f32 v10, v10, s14, v41
	v_med3_f32 v11, v11, s14, v41
	v_med3_f32 v2, v2, s14, v41
	v_med3_f32 v3, v3, s14, v41
	s_add_u32 s6, s6, s19
	v_cvt_scalef32_pk_fp4_f32 v14, v10, v11, 1.0 op_sel:[0,0,1,1]
	v_cvt_scalef32_pk_fp4_f32 v15, v2, v3, 1.0 op_sel:[0,0,1,1]
	s_addc_u32 s7, s7, 0
	global_store_dwordx2 v34, v[14:15], s[6:7]
	s_and_saveexec_b64 s[6:7], s[4:5]
	s_cbranch_execz .LBB0_81
	s_and_b64 s[2:3], s[2:3], exec
	s_cselect_b32 s2, s16, 0x1d00000
	s_add_u32 s2, s82, s2
	s_addc_u32 s3, s83, 0
	s_lshl_b32 s18, s18, 3
	v_mul_f32_e32 v2, 0x3e124925, v42
	v_mov_b32_e32 v3, s18
	global_store_dword v3, v2, s[2:3]
	s_branch .LBB0_81

; #define GAS __attribute__((address_space(1)))
; #define Q4(x) fminf(fmaxf((x) * sc, -6.f), 6.f)
; #define Q4(x) fminf(fmaxf((x) * sc, -6.f), 6.f)
; __device__ __forceinline__ void table_row_to_fp4(const f32x4 (&v)[4], int lane, bool isv, int r, unsigned char* ws) {
;     float m = 0.f;
; #pragma unroll
;     for (int j = 0; j < 4; ++j) m = fmaxf(fmaxf(m, fmaxf(fabsf(v[j].x), fabsf(v[j].y))), fmaxf(fabsf(v[j].z), fabsf(v[j].w)));
; #pragma unroll
;     for (int o = 1; o < 64; o <<= 1) m = fmaxf(m, __shfl_xor(m, o));
;     m = fmaxf(m, 1e-30f);
;     const float sc = 7.f / m;
;     unsigned w0 = 0u, w1 = 0u;
;     ...
;     w0 = __builtin_amdgcn_cvt_scalef32_pk_fp4_f32(w0, Q4(v[0].x), Q4(v[0].y), 1.0f, 0); w0 = __builtin_amdgcn_cvt_scalef32_pk_fp4_f32(w0, Q4(v[0].z), Q4(v[0].w), 1.0f, 1);
;     w0 = __builtin_amdgcn_cvt_scalef32_pk_fp4_f32(w0, Q4(v[1].x), Q4(v[1].y), 1.0f, 2); w0 = __builtin_amdgcn_cvt_scalef32_pk_fp4_f32(w0, Q4(v[1].z), Q4(v[1].w), 1.0f, 3);
;     w1 = __builtin_amdgcn_cvt_scalef32_pk_fp4_f32(w1, Q4(v[2].x), Q4(v[2].y), 1.0f, 0); w1 = __builtin_amdgcn_cvt_scalef32_pk_fp4_f32(w1, Q4(v[2].z), Q4(v[2].w), 1.0f, 1);
;     w1 = __builtin_amdgcn_cvt_scalef32_pk_fp4_f32(w1, Q4(v[3].x), Q4(v[3].y), 1.0f, 2); w1 = __builtin_amdgcn_cvt_scalef32_pk_fp4_f32(w1, Q4(v[3].z), Q4(v[3].w), 1.0f, 3);
;     ...
;     *((GAS v2u*)(ws + (isv ? WS_V8 : WS_U8) + (size_t)r * 512) + lane) = (v2u){w0, w1};
;     if (lane == 0) ((float*)(ws + (isv ? WS_DQV : WS_DQU)))[r] = m * (1.f / 7.f);
; __device__ __forceinline__ void barrier_side_convert(int k, const float* U, const float* V, unsigned char* ws) {
;     ...
;         if (j < RB && g0 + j < glim) { const int g = g0 + j, tb = g >> 14, r = NEXP * (tb >> 1) + (g & (NEXP - 1)); const GAS f32x4* src = (const GAS f32x4*)(((tb & 1) ? V : U) + (size_t)r * D) + 4 * lane;
; #pragma unroll
;             for (int q = 0; q < 4; ++q) v[jj][q] = src[q]; } }
; #pragma unroll
;     for (int jj = 0; jj < 3; ++jj) { const int j = wave - 1 + 7 * jj;
;         if (j < RB && g0 + j < glim) { const int g = g0 + j, tb = g >> 14, r = NEXP * (tb >> 1) + (g & (NEXP - 1)); table_row_to_fp4(v[jj], lane, (tb & 1) != 0, r, ws); } }
.LBB0_150:
	s_andn2_b64 vcc, exec, s[4:5]
	v_cmp_eq_u32_e64 s[4:5], 0, v1
	s_cbranch_vccnz .LBB0_155
	s_add_i32 s2, s2, s14
	s_cmpk_gt_i32 s2, 0x7fff
	s_cbranch_scc1 .LBB0_155
	s_waitcnt vmcnt(0)
	v_max_f32_e64 v50, |v47|, |v47|
	v_max_f32_e64 v51, |v46|, |v46|
	v_max_f32_e32 v50, v51, v50
	v_max_f32_e64 v51, |v49|, |v49|
	v_max_f32_e64 v52, |v48|, |v48|
	v_max_f32_e32 v51, v52, v51
	v_max3_f32 v50, v50, 0, v51
	v_max_f32_e64 v51, |v43|, |v43|
	v_max_f32_e64 v52, |v42|, |v42|
	v_max_f32_e32 v51, v52, v51
	v_max_f32_e64 v52, |v45|, |v45|
	v_max_f32_e64 v53, |v44|, |v44|
	v_max_f32_e32 v52, v53, v52
	v_max3_f32 v50, v50, v51, v52
	v_max_f32_e64 v51, |v39|, |v39|
	v_max_f32_e64 v52, |v38|, |v38|
	v_max_f32_e32 v51, v52, v51
	v_max_f32_e64 v52, |v41|, |v41|
	v_max_f32_e64 v53, |v40|, |v40|
	v_max_f32_e32 v52, v53, v52
	v_max3_f32 v50, v50, v51, v52
	v_max_f32_e64 v51, |v35|, |v35|
	v_max_f32_e64 v52, |v34|, |v34|
	v_max_f32_e32 v51, v52, v51
	v_max_f32_e64 v52, |v37|, |v37|
	v_max_f32_e64 v53, |v36|, |v36|
	v_max_f32_e32 v52, v53, v52
	v_max3_f32 v50, v50, v51, v52
	v_mbcnt_lo_u32_b32 v51, -1, 0
	v_mbcnt_hi_u32_b32 v51, -1, v51
	v_and_b32_e32 v52, 64, v51
	v_add_u32_e32 v52, 64, v52
	v_xor_b32_e32 v53, 1, v51
	v_cmp_lt_i32_e32 vcc, v53, v52
	s_mov_b32 s10, 0xda24260
	s_mov_b32 s17, 0x40e00000
	v_cndmask_b32_e32 v53, v51, v53, vcc
	v_lshlrev_b32_e32 v53, 2, v53
	ds_bpermute_b32 v53, v53, v50
	s_ashr_i32 s3, s2, 1
	s_and_b32 s3, s3, 0xffffc000
	s_and_b32 s12, s2, 0x3fff
	s_waitcnt lgkmcnt(0)
	v_max_f32_e32 v53, v53, v53
	v_max_f32_e32 v50, v50, v53
	v_xor_b32_e32 v53, 2, v51
	v_cmp_lt_i32_e32 vcc, v53, v52
	s_nop 1
	v_cndmask_b32_e32 v53, v51, v53, vcc
	v_lshlrev_b32_e32 v53, 2, v53
	ds_bpermute_b32 v53, v53, v50
	s_waitcnt lgkmcnt(0)
	v_max_f32_e32 v53, v53, v53
	v_max_f32_e32 v50, v50, v53
	v_xor_b32_e32 v53, 4, v51
	v_cmp_lt_i32_e32 vcc, v53, v52
	s_nop 1
	v_cndmask_b32_e32 v53, v51, v53, vcc
	v_lshlrev_b32_e32 v53, 2, v53
	ds_bpermute_b32 v53, v53, v50
	s_waitcnt lgkmcnt(0)
	v_max_f32_e32 v53, v53, v53
	v_max_f32_e32 v50, v50, v53
	v_xor_b32_e32 v53, 8, v51
	v_cmp_lt_i32_e32 vcc, v53, v52
	s_nop 1
	v_cndmask_b32_e32 v53, v51, v53, vcc
	v_lshlrev_b32_e32 v53, 2, v53
	ds_bpermute_b32 v53, v53, v50
	s_waitcnt lgkmcnt(0)
	v_max_f32_e32 v53, v53, v53
	v_max_f32_e32 v50, v50, v53
	v_xor_b32_e32 v53, 16, v51
	v_cmp_lt_i32_e32 vcc, v53, v52
	s_nop 1
	v_cndmask_b32_e32 v53, v51, v53, vcc
	v_lshlrev_b32_e32 v53, 2, v53
	ds_bpermute_b32 v53, v53, v50
	s_waitcnt lgkmcnt(0)
	v_max_f32_e32 v53, v53, v53
	v_max_f32_e32 v50, v50, v53
	v_xor_b32_e32 v53, 32, v51
	v_cmp_lt_i32_e32 vcc, v53, v52
	s_nop 1
	v_cndmask_b32_e32 v51, v51, v53, vcc
	v_lshlrev_b32_e32 v51, 2, v51
	ds_bpermute_b32 v51, v51, v50
	s_waitcnt lgkmcnt(0)
	v_max3_f32 v50, v50, v51, s10
	v_div_scale_f32 v51, s[10:11], v50, v50, s17
	v_rcp_f32_e32 v52, v51
	s_or_b32 s10, s3, s12
	s_bitcmp0_b32 s2, 14
	s_mov_b32 s2, 0xc0c00000
	v_fma_f32 v53, -v51, v52, 1.0
	v_fmac_f32_e32 v52, v53, v52
	v_div_scale_f32 v53, vcc, s17, v50, s17
	v_mul_f32_e32 v54, v53, v52
	v_fma_f32 v55, -v51, v54, v53
	v_fmac_f32_e32 v54, v55, v52
	v_fma_f32 v51, -v51, v54, v53
	v_div_fmas_f32 v51, v51, v52, v54
	v_div_fixup_f32 v51, v51, v50, s17
	v_mul_f32_e32 v46, v46, v51
	v_mov_b32_e32 v54, 0x40c00000
	v_med3_f32 v53, v46, s2, v54
	v_mul_f32_e32 v46, v47, v51
	v_med3_f32 v47, v46, s2, v54
	v_mov_b32_e32 v52, 0
	v_mul_f32_e32 v38, v38, v51
	v_mul_f32_e32 v39, v39, v51
	v_cvt_scalef32_pk_fp4_f32 v52, v53, v47, 1.0
	v_med3_f32 v38, v38, s2, v54
	v_med3_f32 v39, v39, s2, v54
	v_mov_b32_e32 v53, 0
	v_mul_f32_e32 v47, v48, v51
	v_mul_f32_e32 v48, v49, v51
	v_cvt_scalef32_pk_fp4_f32 v53, v38, v39, 1.0
	v_mul_f32_e32 v38, v40, v51
	v_mul_f32_e32 v39, v41, v51
	v_med3_f32 v47, v47, s2, v54
	v_med3_f32 v48, v48, s2, v54
	v_mul_f32_e32 v42, v42, v51
	v_mul_f32_e32 v43, v43, v51
	v_med3_f32 v38, v38, s2, v54
	v_med3_f32 v39, v39, s2, v54
	v_mul_f32_e32 v34, v34, v51
	v_mul_f32_e32 v35, v35, v51
	v_cvt_scalef32_pk_fp4_f32 v52, v47, v48, 1.0 op_sel:[0,0,1,0]
	v_med3_f32 v42, v42, s2, v54
	v_med3_f32 v43, v43, s2, v54
	v_cvt_scalef32_pk_fp4_f32 v53, v38, v39, 1.0 op_sel:[0,0,1,0]
	v_med3_f32 v34, v34, s2, v54
	v_med3_f32 v35, v35, s2, v54
	s_cselect_b64 s[12:13], -1, 0
	v_cvt_scalef32_pk_fp4_f32 v52, v42, v43, 1.0 op_sel:[0,0,0,1]
	v_mul_f32_e32 v42, v44, v51
	v_mul_f32_e32 v43, v45, v51
	v_cvt_scalef32_pk_fp4_f32 v53, v34, v35, 1.0 op_sel:[0,0,0,1]
	v_mul_f32_e32 v34, v36, v51
	v_mul_f32_e32 v35, v37, v51
	v_med3_f32 v42, v42, s2, v54
	v_med3_f32 v43, v43, s2, v54
	v_med3_f32 v34, v34, s2, v54
	v_med3_f32 v35, v35, s2, v54
	s_brev_b32 s11, 64
	s_and_b64 s[2:3], s[12:13], exec
	s_cselect_b32 s2, s11, 0x4000000
	s_add_u32 s17, s82, s2
	s_addc_u32 s18, s83, 0
	s_ashr_i32 s11, s10, 31
	s_lshl_b64 s[2:3], s[10:11], 9
	s_add_u32 s2, s17, s2
	v_mov_b32_e32 v46, 0
	v_cvt_scalef32_pk_fp4_f32 v52, v42, v43, 1.0 op_sel:[0,0,1,1]
	v_cvt_scalef32_pk_fp4_f32 v53, v34, v35, 1.0 op_sel:[0,0,1,1]
	s_addc_u32 s3, s18, s3
	v_lshlrev_b32_e32 v34, 3, v1
	global_store_dwordx2 v34, v[52:53], s[2:3]
	s_and_saveexec_b64 s[2:3], s[4:5]
	s_cbranch_execz .LBB0_154
	s_mov_b32 s17, 0x1d00000
	s_and_b64 s[12:13], s[12:13], exec
	s_cselect_b32 s12, s17, 0x1d00004
	s_add_u32 s12, s82, s12
	s_addc_u32 s13, s83, 0
	s_lshl_b64 s[10:11], s[10:11], 3
	s_add_u32 s10, s12, s10
	v_mul_f32_e32 v34, 0x3e124925, v50
	s_addc_u32 s11, s13, s11
	global_store_dword v46, v34, s[10:11]

; #define GAS __attribute__((address_space(1)))
; #define Q4(x) fminf(fmaxf((x) * sc, -6.f), 6.f)
; #define Q4(x) fminf(fmaxf((x) * sc, -6.f), 6.f)
; __device__ __forceinline__ void table_row_to_fp4(const f32x4 (&v)[4], int lane, bool isv, int r, unsigned char* ws) {
;     float m = 0.f;
; #pragma unroll
;     for (int j = 0; j < 4; ++j) m = fmaxf(fmaxf(m, fmaxf(fabsf(v[j].x), fabsf(v[j].y))), fmaxf(fabsf(v[j].z), fabsf(v[j].w)));
; #pragma unroll
;     for (int o = 1; o < 64; o <<= 1) m = fmaxf(m, __shfl_xor(m, o));
;     m = fmaxf(m, 1e-30f);
;     const float sc = 7.f / m;
;     unsigned w0 = 0u, w1 = 0u;
;     ...
;     w0 = __builtin_amdgcn_cvt_scalef32_pk_fp4_f32(w0, Q4(v[0].x), Q4(v[0].y), 1.0f, 0); w0 = __builtin_amdgcn_cvt_scalef32_pk_fp4_f32(w0, Q4(v[0].z), Q4(v[0].w), 1.0f, 1);
;     w0 = __builtin_amdgcn_cvt_scalef32_pk_fp4_f32(w0, Q4(v[1].x), Q4(v[1].y), 1.0f, 2); w0 = __builtin_amdgcn_cvt_scalef32_pk_fp4_f32(w0, Q4(v[1].z), Q4(v[1].w), 1.0f, 3);
;     w1 = __builtin_amdgcn_cvt_scalef32_pk_fp4_f32(w1, Q4(v[2].x), Q4(v[2].y), 1.0f, 0); w1 = __builtin_amdgcn_cvt_scalef32_pk_fp4_f32(w1, Q4(v[2].z), Q4(v[2].w), 1.0f, 1);
;     w1 = __builtin_amdgcn_cvt_scalef32_pk_fp4_f32(w1, Q4(v[3].x), Q4(v[3].y), 1.0f, 2); w1 = __builtin_amdgcn_cvt_scalef32_pk_fp4_f32(w1, Q4(v[3].z), Q4(v[3].w), 1.0f, 3);
;     ...
;     *((GAS v2u*)(ws + (isv ? WS_V8 : WS_U8) + (size_t)r * 512) + lane) = (v2u){w0, w1};
;     if (lane == 0) ((float*)(ws + (isv ? WS_DQV : WS_DQU)))[r] = m * (1.f / 7.f);
; __device__ __forceinline__ void barrier_side_convert(int k, const float* U, const float* V, unsigned char* ws) {
;     ...
;         if (j < RB && g0 + j < glim) { const int g = g0 + j, tb = g >> 14, r = NEXP * (tb >> 1) + (g & (NEXP - 1)); const GAS f32x4* src = (const GAS f32x4*)(((tb & 1) ? V : U) + (size_t)r * D) + 4 * lane;
; #pragma unroll
;             for (int q = 0; q < 4; ++q) v[jj][q] = src[q]; } }
; #pragma unroll
;     for (int jj = 0; jj < 3; ++jj) { const int j = wave - 1 + 7 * jj;
;         if (j < RB && g0 + j < glim) { const int g = g0 + j, tb = g >> 14, r = NEXP * (tb >> 1) + (g & (NEXP - 1)); table_row_to_fp4(v[jj], lane, (tb & 1) != 0, r, ws); } }
.LBB0_155:
	s_andn2_b64 vcc, exec, s[8:9]
	s_cbranch_vccnz .LBB0_160
	s_add_i32 s16, s16, s14
	s_cmpk_gt_i32 s16, 0x7fff
	s_cbranch_scc1 .LBB0_160
	s_waitcnt vmcnt(0)
	v_max_f32_e64 v34, |v31|, |v31|
	v_max_f32_e64 v35, |v30|, |v30|
	v_max_f32_e32 v34, v35, v34
	v_max_f32_e64 v35, |v33|, |v33|
	v_max_f32_e64 v36, |v32|, |v32|
	v_max_f32_e32 v35, v36, v35
	v_max3_f32 v34, v34, 0, v35
	v_max_f32_e64 v35, |v27|, |v27|
	v_max_f32_e64 v36, |v26|, |v26|
	v_max_f32_e32 v35, v36, v35
	v_max_f32_e64 v36, |v29|, |v29|
	v_max_f32_e64 v37, |v28|, |v28|
	v_max_f32_e32 v36, v37, v36
	v_max3_f32 v34, v34, v35, v36
	v_max_f32_e64 v35, |v23|, |v23|
	v_max_f32_e64 v36, |v22|, |v22|
	v_max_f32_e32 v35, v36, v35
	v_max_f32_e64 v36, |v25|, |v25|
	v_max_f32_e64 v37, |v24|, |v24|
	v_max_f32_e32 v36, v37, v36
	v_max3_f32 v34, v34, v35, v36
	v_max_f32_e64 v35, |v19|, |v19|
	v_max_f32_e64 v36, |v18|, |v18|
	v_max_f32_e32 v35, v36, v35
	v_max_f32_e64 v36, |v21|, |v21|
	v_max_f32_e64 v37, |v20|, |v20|
	v_max_f32_e32 v36, v37, v36
	v_max3_f32 v34, v34, v35, v36
	v_mbcnt_lo_u32_b32 v35, -1, 0
	v_mbcnt_hi_u32_b32 v35, -1, v35
	v_and_b32_e32 v36, 64, v35
	v_add_u32_e32 v36, 64, v36
	v_xor_b32_e32 v37, 1, v35
	v_cmp_lt_i32_e32 vcc, v37, v36
	s_ashr_i32 s2, s16, 1
	s_and_b32 s8, s2, 0xffffc000
	v_cndmask_b32_e32 v37, v35, v37, vcc
	v_lshlrev_b32_e32 v37, 2, v37
	ds_bpermute_b32 v37, v37, v34
	s_mov_b32 s2, 0xda24260
	s_mov_b32 s12, 0x40e00000
	s_and_b32 s9, s16, 0x3fff
	s_or_b32 s8, s8, s9
	s_waitcnt lgkmcnt(0)
	v_max_f32_e32 v37, v37, v37
	v_max_f32_e32 v34, v34, v37
	v_xor_b32_e32 v37, 2, v35
	v_cmp_lt_i32_e32 vcc, v37, v36
	s_bitcmp0_b32 s16, 14
	s_cselect_b64 s[10:11], -1, 0
	v_cndmask_b32_e32 v37, v35, v37, vcc
	v_lshlrev_b32_e32 v37, 2, v37
	ds_bpermute_b32 v37, v37, v34
	s_brev_b32 s9, 64
	s_waitcnt lgkmcnt(0)
	v_max_f32_e32 v37, v37, v37
	v_max_f32_e32 v34, v34, v37
	v_xor_b32_e32 v37, 4, v35
	v_cmp_lt_i32_e32 vcc, v37, v36
	s_nop 1
	v_cndmask_b32_e32 v37, v35, v37, vcc
	v_lshlrev_b32_e32 v37, 2, v37
	ds_bpermute_b32 v37, v37, v34
	s_waitcnt lgkmcnt(0)
	v_max_f32_e32 v37, v37, v37
	v_max_f32_e32 v34, v34, v37
	v_xor_b32_e32 v37, 8, v35
	v_cmp_lt_i32_e32 vcc, v37, v36
	s_nop 1
	v_cndmask_b32_e32 v37, v35, v37, vcc
	v_lshlrev_b32_e32 v37, 2, v37
	ds_bpermute_b32 v37, v37, v34
	s_waitcnt lgkmcnt(0)
	v_max_f32_e32 v37, v37, v37
	v_max_f32_e32 v34, v34, v37
	v_xor_b32_e32 v37, 16, v35
	v_cmp_lt_i32_e32 vcc, v37, v36
	s_nop 1
	v_cndmask_b32_e32 v37, v35, v37, vcc
	v_lshlrev_b32_e32 v37, 2, v37
	ds_bpermute_b32 v37, v37, v34
	s_waitcnt lgkmcnt(0)
	v_max_f32_e32 v37, v37, v37
	v_max_f32_e32 v34, v34, v37
	v_xor_b32_e32 v37, 32, v35
	v_cmp_lt_i32_e32 vcc, v37, v36
	s_nop 1
	v_cndmask_b32_e32 v35, v35, v37, vcc
	v_lshlrev_b32_e32 v35, 2, v35
	ds_bpermute_b32 v35, v35, v34
	s_waitcnt lgkmcnt(0)
	v_max3_f32 v34, v34, v35, s2
	v_div_scale_f32 v35, s[2:3], v34, v34, s12
	v_rcp_f32_e32 v36, v35
	s_mov_b32 s2, 0xc0c00000
	v_fma_f32 v37, -v35, v36, 1.0
	v_fmac_f32_e32 v36, v37, v36
	v_div_scale_f32 v37, vcc, s12, v34, s12
	v_mul_f32_e32 v38, v37, v36
	v_fma_f32 v39, -v35, v38, v37
	v_fmac_f32_e32 v38, v39, v36
	v_fma_f32 v35, -v35, v38, v37
	v_div_fmas_f32 v35, v35, v36, v38
	v_div_fixup_f32 v35, v35, v34, s12
	v_mul_f32_e32 v30, v30, v35
	v_mov_b32_e32 v38, 0x40c00000
	v_med3_f32 v37, v30, s2, v38
	v_mul_f32_e32 v30, v31, v35
	v_med3_f32 v31, v30, s2, v38
	v_mov_b32_e32 v36, 0
	v_mul_f32_e32 v22, v22, v35
	v_mul_f32_e32 v23, v23, v35
	v_cvt_scalef32_pk_fp4_f32 v36, v37, v31, 1.0
	v_med3_f32 v22, v22, s2, v38
	v_med3_f32 v23, v23, s2, v38
	v_mov_b32_e32 v37, 0
	v_mul_f32_e32 v31, v32, v35
	v_mul_f32_e32 v32, v33, v35
	v_cvt_scalef32_pk_fp4_f32 v37, v22, v23, 1.0
	v_mul_f32_e32 v22, v24, v35
	v_mul_f32_e32 v23, v25, v35
	v_med3_f32 v31, v31, s2, v38
	v_med3_f32 v32, v32, s2, v38
	v_mul_f32_e32 v26, v26, v35
	v_mul_f32_e32 v27, v27, v35
	v_med3_f32 v22, v22, s2, v38
	v_med3_f32 v23, v23, s2, v38
	v_mul_f32_e32 v18, v18, v35
	v_mul_f32_e32 v19, v19, v35
	v_cvt_scalef32_pk_fp4_f32 v36, v31, v32, 1.0 op_sel:[0,0,1,0]
	v_med3_f32 v26, v26, s2, v38
	v_med3_f32 v27, v27, s2, v38
	v_cvt_scalef32_pk_fp4_f32 v37, v22, v23, 1.0 op_sel:[0,0,1,0]
	v_med3_f32 v18, v18, s2, v38
	v_med3_f32 v19, v19, s2, v38
	v_cvt_scalef32_pk_fp4_f32 v36, v26, v27, 1.0 op_sel:[0,0,0,1]
	v_mul_f32_e32 v26, v28, v35
	v_mul_f32_e32 v27, v29, v35
	v_cvt_scalef32_pk_fp4_f32 v37, v18, v19, 1.0 op_sel:[0,0,0,1]
	v_mul_f32_e32 v18, v20, v35
	v_mul_f32_e32 v19, v21, v35
	v_med3_f32 v26, v26, s2, v38
	v_med3_f32 v27, v27, s2, v38
	v_med3_f32 v18, v18, s2, v38
	v_med3_f32 v19, v19, s2, v38
	s_and_b64 s[2:3], s[10:11], exec
	s_cselect_b32 s2, s9, 0x4000000
	s_add_u32 s12, s82, s2
	s_addc_u32 s13, s83, 0
	s_ashr_i32 s9, s8, 31
	s_lshl_b64 s[2:3], s[8:9], 9
	s_add_u32 s2, s12, s2
	v_mov_b32_e32 v30, 0
	v_cvt_scalef32_pk_fp4_f32 v36, v26, v27, 1.0 op_sel:[0,0,1,1]
	v_cvt_scalef32_pk_fp4_f32 v37, v18, v19, 1.0 op_sel:[0,0,1,1]
	s_addc_u32 s3, s13, s3
	v_lshlrev_b32_e32 v18, 3, v1
	global_store_dwordx2 v18, v[36:37], s[2:3]
	s_and_saveexec_b64 s[2:3], s[4:5]
	s_cbranch_execz .LBB0_159
	s_mov_b32 s12, 0x1d00000
	s_and_b64 s[10:11], s[10:11], exec
	s_cselect_b32 s10, s12, 0x1d00004
	s_add_u32 s10, s82, s10
	s_addc_u32 s11, s83, 0
	s_lshl_b64 s[8:9], s[8:9], 3
	s_add_u32 s8, s10, s8
	v_mul_f32_e32 v18, 0x3e124925, v34
	s_addc_u32 s9, s11, s9
	global_store_dword v30, v18, s[8:9]

; #define GAS __attribute__((address_space(1)))
; #define Q4(x) fminf(fmaxf((x) * sc, -6.f), 6.f)
; #define Q4(x) fminf(fmaxf((x) * sc, -6.f), 6.f)
; __device__ __forceinline__ void table_row_to_fp4(const f32x4 (&v)[4], int lane, bool isv, int r, unsigned char* ws) {
;     float m = 0.f;
; #pragma unroll
;     for (int j = 0; j < 4; ++j) m = fmaxf(fmaxf(m, fmaxf(fabsf(v[j].x), fabsf(v[j].y))), fmaxf(fabsf(v[j].z), fabsf(v[j].w)));
; #pragma unroll
;     for (int o = 1; o < 64; o <<= 1) m = fmaxf(m, __shfl_xor(m, o));
;     m = fmaxf(m, 1e-30f);
;     const float sc = 7.f / m;
;     unsigned w0 = 0u, w1 = 0u;
;     ...
;     w0 = __builtin_amdgcn_cvt_scalef32_pk_fp4_f32(w0, Q4(v[0].x), Q4(v[0].y), 1.0f, 0); w0 = __builtin_amdgcn_cvt_scalef32_pk_fp4_f32(w0, Q4(v[0].z), Q4(v[0].w), 1.0f, 1);
;     w0 = __builtin_amdgcn_cvt_scalef32_pk_fp4_f32(w0, Q4(v[1].x), Q4(v[1].y), 1.0f, 2); w0 = __builtin_amdgcn_cvt_scalef32_pk_fp4_f32(w0, Q4(v[1].z), Q4(v[1].w), 1.0f, 3);
;     w1 = __builtin_amdgcn_cvt_scalef32_pk_fp4_f32(w1, Q4(v[2].x), Q4(v[2].y), 1.0f, 0); w1 = __builtin_amdgcn_cvt_scalef32_pk_fp4_f32(w1, Q4(v[2].z), Q4(v[2].w), 1.0f, 1);
;     w1 = __builtin_amdgcn_cvt_scalef32_pk_fp4_f32(w1, Q4(v[3].x), Q4(v[3].y), 1.0f, 2); w1 = __builtin_amdgcn_cvt_scalef32_pk_fp4_f32(w1, Q4(v[3].z), Q4(v[3].w), 1.0f, 3);
;     ...
;     *((GAS v2u*)(ws + (isv ? WS_V8 : WS_U8) + (size_t)r * 512) + lane) = (v2u){w0, w1};
;     if (lane == 0) ((float*)(ws + (isv ? WS_DQV : WS_DQU)))[r] = m * (1.f / 7.f);
; __device__ __forceinline__ void barrier_side_convert(int k, const float* U, const float* V, unsigned char* ws) {
;     ...
;         if (j < RB && g0 + j < glim) { const int g = g0 + j, tb = g >> 14, r = NEXP * (tb >> 1) + (g & (NEXP - 1)); const GAS f32x4* src = (const GAS f32x4*)(((tb & 1) ? V : U) + (size_t)r * D) + 4 * lane;
; #pragma unroll
;             for (int q = 0; q < 4; ++q) v[jj][q] = src[q]; } }
; #pragma unroll
;     for (int jj = 0; jj < 3; ++jj) { const int j = wave - 1 + 7 * jj;
;         if (j < RB && g0 + j < glim) { const int g = g0 + j, tb = g >> 14, r = NEXP * (tb >> 1) + (g & (NEXP - 1)); table_row_to_fp4(v[jj], lane, (tb & 1) != 0, r, ws); } }
.LBB0_160:
	s_andn2_b64 vcc, exec, s[6:7]
	s_cbranch_vccnz .LBB0_165
	s_add_i32 s15, s15, s14
	s_cmpk_gt_i32 s15, 0x7fff
	s_cbranch_scc1 .LBB0_165
	s_waitcnt vmcnt(0)
	v_max_f32_e64 v18, |v15|, |v15|
	v_max_f32_e64 v19, |v14|, |v14|
	v_max_f32_e32 v18, v19, v18
	v_max_f32_e64 v19, |v17|, |v17|
	v_max_f32_e64 v20, |v16|, |v16|
	v_max_f32_e32 v19, v20, v19
	v_max3_f32 v18, v18, 0, v19
	v_max_f32_e64 v19, |v11|, |v11|
	v_max_f32_e64 v20, |v10|, |v10|
	v_max_f32_e32 v19, v20, v19
	v_max_f32_e64 v20, |v13|, |v13|
	v_max_f32_e64 v21, |v12|, |v12|
	v_max_f32_e32 v20, v21, v20
	v_max3_f32 v18, v18, v19, v20
	v_max_f32_e64 v19, |v7|, |v7|
	v_max_f32_e64 v20, |v6|, |v6|
	v_max_f32_e32 v19, v20, v19
	v_max_f32_e64 v20, |v9|, |v9|
	v_max_f32_e64 v21, |v8|, |v8|
	v_max_f32_e32 v20, v21, v20
	v_max3_f32 v18, v18, v19, v20
	v_max_f32_e64 v19, |v3|, |v3|
	v_max_f32_e64 v20, |v2|, |v2|
	v_max_f32_e32 v19, v20, v19
	v_max_f32_e64 v20, |v5|, |v5|
	v_max_f32_e64 v21, |v4|, |v4|
	v_max_f32_e32 v20, v21, v20
	v_max3_f32 v18, v18, v19, v20
	v_mbcnt_lo_u32_b32 v19, -1, 0
	v_mbcnt_hi_u32_b32 v19, -1, v19
	v_and_b32_e32 v20, 64, v19
	v_add_u32_e32 v20, 64, v20
	v_xor_b32_e32 v21, 1, v19
	v_cmp_lt_i32_e32 vcc, v21, v20
	s_ashr_i32 s2, s15, 1
	s_and_b32 s6, s2, 0xffffc000
	v_cndmask_b32_e32 v21, v19, v21, vcc
	v_lshlrev_b32_e32 v21, 2, v21
	ds_bpermute_b32 v21, v21, v18
	s_mov_b32 s2, 0xda24260
	s_mov_b32 s10, 0x40e00000
	s_and_b32 s7, s15, 0x3fff
	s_or_b32 s6, s6, s7
	s_waitcnt lgkmcnt(0)
	v_max_f32_e32 v21, v21, v21
	v_max_f32_e32 v18, v18, v21
	v_xor_b32_e32 v21, 2, v19
	v_cmp_lt_i32_e32 vcc, v21, v20
	s_bitcmp0_b32 s15, 14
	s_cselect_b64 s[8:9], -1, 0
	v_cndmask_b32_e32 v21, v19, v21, vcc
	v_lshlrev_b32_e32 v21, 2, v21
	ds_bpermute_b32 v21, v21, v18
	s_brev_b32 s7, 64
	v_lshlrev_b32_e32 v1, 3, v1
	s_waitcnt lgkmcnt(0)
	v_max_f32_e32 v21, v21, v21
	v_max_f32_e32 v18, v18, v21
	v_xor_b32_e32 v21, 4, v19
	v_cmp_lt_i32_e32 vcc, v21, v20
	s_nop 1
	v_cndmask_b32_e32 v21, v19, v21, vcc
	v_lshlrev_b32_e32 v21, 2, v21
	ds_bpermute_b32 v21, v21, v18
	s_waitcnt lgkmcnt(0)
	v_max_f32_e32 v21, v21, v21
	v_max_f32_e32 v18, v18, v21
	v_xor_b32_e32 v21, 8, v19
	v_cmp_lt_i32_e32 vcc, v21, v20
	s_nop 1
	v_cndmask_b32_e32 v21, v19, v21, vcc
	v_lshlrev_b32_e32 v21, 2, v21
	ds_bpermute_b32 v21, v21, v18
	s_waitcnt lgkmcnt(0)
	v_max_f32_e32 v21, v21, v21
	v_max_f32_e32 v18, v18, v21
	v_xor_b32_e32 v21, 16, v19
	v_cmp_lt_i32_e32 vcc, v21, v20
	s_nop 1
	v_cndmask_b32_e32 v21, v19, v21, vcc
	v_lshlrev_b32_e32 v21, 2, v21
	ds_bpermute_b32 v21, v21, v18
	s_waitcnt lgkmcnt(0)
	v_max_f32_e32 v21, v21, v21
	v_max_f32_e32 v18, v18, v21
	v_xor_b32_e32 v21, 32, v19
	v_cmp_lt_i32_e32 vcc, v21, v20
	s_nop 1
	v_cndmask_b32_e32 v19, v19, v21, vcc
	v_lshlrev_b32_e32 v19, 2, v19
	ds_bpermute_b32 v19, v19, v18
	s_waitcnt lgkmcnt(0)
	v_max3_f32 v18, v18, v19, s2
	v_div_scale_f32 v19, s[2:3], v18, v18, s10
	v_rcp_f32_e32 v20, v19
	s_mov_b32 s2, 0xc0c00000
	v_fma_f32 v21, -v19, v20, 1.0
	v_fmac_f32_e32 v20, v21, v20
	v_div_scale_f32 v21, vcc, s10, v18, s10
	v_mul_f32_e32 v22, v21, v20
	v_fma_f32 v23, -v19, v22, v21
	v_fmac_f32_e32 v22, v23, v20
	v_fma_f32 v19, -v19, v22, v21
	v_div_fmas_f32 v19, v19, v20, v22
	v_div_fixup_f32 v19, v19, v18, s10
	v_mul_f32_e32 v14, v14, v19
	v_mov_b32_e32 v22, 0x40c00000
	v_med3_f32 v21, v14, s2, v22
	v_mul_f32_e32 v14, v15, v19
	v_med3_f32 v15, v14, s2, v22
	v_mov_b32_e32 v20, 0
	v_mul_f32_e32 v6, v6, v19
	v_mul_f32_e32 v7, v7, v19
	v_cvt_scalef32_pk_fp4_f32 v20, v21, v15, 1.0
	v_med3_f32 v6, v6, s2, v22
	v_med3_f32 v7, v7, s2, v22
	v_mov_b32_e32 v21, 0
	v_mul_f32_e32 v15, v16, v19
	v_mul_f32_e32 v16, v17, v19
	v_cvt_scalef32_pk_fp4_f32 v21, v6, v7, 1.0
	v_mul_f32_e32 v6, v8, v19
	v_mul_f32_e32 v7, v9, v19
	v_med3_f32 v15, v15, s2, v22
	v_med3_f32 v16, v16, s2, v22
	v_mul_f32_e32 v10, v10, v19
	v_mul_f32_e32 v11, v11, v19
	v_med3_f32 v6, v6, s2, v22
	v_med3_f32 v7, v7, s2, v22
	v_mul_f32_e32 v2, v2, v19
	v_mul_f32_e32 v3, v3, v19
	v_cvt_scalef32_pk_fp4_f32 v20, v15, v16, 1.0 op_sel:[0,0,1,0]
	v_med3_f32 v10, v10, s2, v22
	v_med3_f32 v11, v11, s2, v22
	v_cvt_scalef32_pk_fp4_f32 v21, v6, v7, 1.0 op_sel:[0,0,1,0]
	v_med3_f32 v2, v2, s2, v22
	v_med3_f32 v3, v3, s2, v22
	v_cvt_scalef32_pk_fp4_f32 v20, v10, v11, 1.0 op_sel:[0,0,0,1]
	v_mul_f32_e32 v10, v12, v19
	v_mul_f32_e32 v11, v13, v19
	v_cvt_scalef32_pk_fp4_f32 v21, v2, v3, 1.0 op_sel:[0,0,0,1]
	v_mul_f32_e32 v2, v4, v19
	v_mul_f32_e32 v3, v5, v19
	v_med3_f32 v10, v10, s2, v22
	v_med3_f32 v11, v11, s2, v22
	v_med3_f32 v2, v2, s2, v22
	v_med3_f32 v3, v3, s2, v22
	s_and_b64 s[2:3], s[8:9], exec
	s_cselect_b32 s2, s7, 0x4000000
	s_add_u32 s10, s82, s2
	s_addc_u32 s11, s83, 0
	s_ashr_i32 s7, s6, 31
	s_lshl_b64 s[2:3], s[6:7], 9
	s_add_u32 s2, s10, s2
	v_mov_b32_e32 v14, 0
	v_cvt_scalef32_pk_fp4_f32 v20, v10, v11, 1.0 op_sel:[0,0,1,1]
	v_cvt_scalef32_pk_fp4_f32 v21, v2, v3, 1.0 op_sel:[0,0,1,1]
	s_addc_u32 s3, s11, s3
	global_store_dwordx2 v1, v[20:21], s[2:3]
	s_and_saveexec_b64 s[2:3], s[4:5]
	s_cbranch_execz .LBB0_164
	s_mov_b32 s10, 0x1d00000
	s_and_b64 s[4:5], s[8:9], exec
	s_cselect_b32 s4, s10, 0x1d00004
	s_add_u32 s8, s82, s4
	s_addc_u32 s9, s83, 0
	s_lshl_b64 s[4:5], s[6:7], 3
	s_add_u32 s4, s8, s4
	v_mul_f32_e32 v1, 0x3e124925, v18
	s_addc_u32 s5, s9, s5
	global_store_dword v14, v1, s[4:5]

; #define GAS __attribute__((address_space(1)))
; #define Q4(x) fminf(fmaxf((x) * sc, -6.f), 6.f)
; #define Q4(x) fminf(fmaxf((x) * sc, -6.f), 6.f)
; __device__ __forceinline__ void table_row_to_fp4(const f32x4 (&v)[4], int lane, bool isv, int r, unsigned char* ws) {
;     float m = 0.f;
; #pragma unroll
;     for (int j = 0; j < 4; ++j) m = fmaxf(fmaxf(m, fmaxf(fabsf(v[j].x), fabsf(v[j].y))), fmaxf(fabsf(v[j].z), fabsf(v[j].w)));
; #pragma unroll
;     for (int o = 1; o < 64; o <<= 1) m = fmaxf(m, __shfl_xor(m, o));
;     m = fmaxf(m, 1e-30f);
;     const float sc = 7.f / m;
;     unsigned w0 = 0u, w1 = 0u;
;     ...
;     w0 = __builtin_amdgcn_cvt_scalef32_pk_fp4_f32(w0, Q4(v[0].x), Q4(v[0].y), 1.0f, 0); w0 = __builtin_amdgcn_cvt_scalef32_pk_fp4_f32(w0, Q4(v[0].z), Q4(v[0].w), 1.0f, 1);
;     w0 = __builtin_amdgcn_cvt_scalef32_pk_fp4_f32(w0, Q4(v[1].x), Q4(v[1].y), 1.0f, 2); w0 = __builtin_amdgcn_cvt_scalef32_pk_fp4_f32(w0, Q4(v[1].z), Q4(v[1].w), 1.0f, 3);
;     w1 = __builtin_amdgcn_cvt_scalef32_pk_fp4_f32(w1, Q4(v[2].x), Q4(v[2].y), 1.0f, 0); w1 = __builtin_amdgcn_cvt_scalef32_pk_fp4_f32(w1, Q4(v[2].z), Q4(v[2].w), 1.0f, 1);
;     w1 = __builtin_amdgcn_cvt_scalef32_pk_fp4_f32(w1, Q4(v[3].x), Q4(v[3].y), 1.0f, 2); w1 = __builtin_amdgcn_cvt_scalef32_pk_fp4_f32(w1, Q4(v[3].z), Q4(v[3].w), 1.0f, 3);
;     ...
;     *((GAS v2u*)(ws + (isv ? WS_V8 : WS_U8) + (size_t)r * 512) + lane) = (v2u){w0, w1};
;     if (lane == 0) ((float*)(ws + (isv ? WS_DQV : WS_DQU)))[r] = m * (1.f / 7.f);
; __device__ __forceinline__ void barrier_side_convert(int k, const float* U, const float* V, unsigned char* ws) {
;     ...
;         if (j < RB && g0 + j < glim) { const int g = g0 + j, tb = g >> 14, r = NEXP * (tb >> 1) + (g & (NEXP - 1)); const GAS f32x4* src = (const GAS f32x4*)(((tb & 1) ? V : U) + (size_t)r * D) + 4 * lane;
; #pragma unroll
;             for (int q = 0; q < 4; ++q) v[jj][q] = src[q]; } }
; #pragma unroll
;     for (int jj = 0; jj < 3; ++jj) { const int j = wave - 1 + 7 * jj;
;         if (j < RB && g0 + j < glim) { const int g = g0 + j, tb = g >> 14, r = NEXP * (tb >> 1) + (g & (NEXP - 1)); table_row_to_fp4(v[jj], lane, (tb & 1) != 0, r, ws); } }
.LBB0_724:
	s_andn2_b64 vcc, exec, s[0:1]
	s_cbranch_vccnz .LBB0_729
	s_add_i32 s15, s15, s14
	s_cmpk_gt_i32 s15, 0x7fff
	s_cbranch_scc1 .LBB0_729
	s_waitcnt vmcnt(0)
	v_max_f32_e64 v18, |v15|, |v15|
	v_max_f32_e64 v19, |v14|, |v14|
	v_max_f32_e32 v18, v19, v18
	v_max_f32_e64 v19, |v17|, |v17|
	v_max_f32_e64 v20, |v16|, |v16|
	v_max_f32_e32 v19, v20, v19
	v_max3_f32 v18, v18, 0, v19
	v_max_f32_e64 v19, |v11|, |v11|
	v_max_f32_e64 v20, |v10|, |v10|
	v_max_f32_e32 v19, v20, v19
	v_max_f32_e64 v20, |v13|, |v13|
	v_max_f32_e64 v21, |v12|, |v12|
	v_max_f32_e32 v20, v21, v20
	v_max3_f32 v18, v18, v19, v20
	v_max_f32_e64 v19, |v7|, |v7|
	v_max_f32_e64 v20, |v6|, |v6|
	v_max_f32_e32 v19, v20, v19
	v_max_f32_e64 v20, |v9|, |v9|
	v_max_f32_e64 v21, |v8|, |v8|
	v_max_f32_e32 v20, v21, v20
	v_max3_f32 v18, v18, v19, v20
	v_max_f32_e64 v19, |v3|, |v3|
	v_max_f32_e64 v20, |v2|, |v2|
	v_max_f32_e32 v19, v20, v19
	v_max_f32_e64 v20, |v5|, |v5|
	v_max_f32_e64 v21, |v4|, |v4|
	v_max_f32_e32 v20, v21, v20
	v_max3_f32 v18, v18, v19, v20
	v_mbcnt_lo_u32_b32 v19, -1, 0
	v_mbcnt_hi_u32_b32 v19, -1, v19
	v_and_b32_e32 v20, 64, v19
	v_add_u32_e32 v20, 64, v20
	v_xor_b32_e32 v21, 1, v19
	v_cmp_lt_i32_e32 vcc, v21, v20
	s_ashr_i32 s0, s15, 1
	s_and_b32 s2, s0, 0xffffc000
	v_cndmask_b32_e32 v21, v19, v21, vcc
	v_lshlrev_b32_e32 v21, 2, v21
	ds_bpermute_b32 v21, v21, v18
	s_mov_b32 s0, 0xda24260
	s_mov_b32 s10, 0x40e00000
	s_and_b32 s3, s15, 0x3fff
	v_lshlrev_b32_e32 v1, 3, v1
	s_waitcnt lgkmcnt(0)
	v_max_f32_e32 v21, v21, v21
	v_max_f32_e32 v18, v18, v21
	v_xor_b32_e32 v21, 2, v19
	v_cmp_lt_i32_e32 vcc, v21, v20
	s_nop 1
	v_cndmask_b32_e32 v21, v19, v21, vcc
	v_lshlrev_b32_e32 v21, 2, v21
	ds_bpermute_b32 v21, v21, v18
	s_waitcnt lgkmcnt(0)
	v_max_f32_e32 v21, v21, v21
	v_max_f32_e32 v18, v18, v21
	v_xor_b32_e32 v21, 4, v19
	v_cmp_lt_i32_e32 vcc, v21, v20
	s_nop 1
	v_cndmask_b32_e32 v21, v19, v21, vcc
	v_lshlrev_b32_e32 v21, 2, v21
	ds_bpermute_b32 v21, v21, v18
	s_waitcnt lgkmcnt(0)
	v_max_f32_e32 v21, v21, v21
	v_max_f32_e32 v18, v18, v21
	v_xor_b32_e32 v21, 8, v19
	v_cmp_lt_i32_e32 vcc, v21, v20
	s_nop 1
	v_cndmask_b32_e32 v21, v19, v21, vcc
	v_lshlrev_b32_e32 v21, 2, v21
	ds_bpermute_b32 v21, v21, v18
	s_waitcnt lgkmcnt(0)
	v_max_f32_e32 v21, v21, v21
	v_max_f32_e32 v18, v18, v21
	v_xor_b32_e32 v21, 16, v19
	v_cmp_lt_i32_e32 vcc, v21, v20
	s_nop 1
	v_cndmask_b32_e32 v21, v19, v21, vcc
	v_lshlrev_b32_e32 v21, 2, v21
	ds_bpermute_b32 v21, v21, v18
	s_waitcnt lgkmcnt(0)
	v_max_f32_e32 v21, v21, v21
	v_max_f32_e32 v18, v18, v21
	v_xor_b32_e32 v21, 32, v19
	v_cmp_lt_i32_e32 vcc, v21, v20
	s_nop 1
	v_cndmask_b32_e32 v19, v19, v21, vcc
	v_lshlrev_b32_e32 v19, 2, v19
	ds_bpermute_b32 v19, v19, v18
	s_waitcnt lgkmcnt(0)
	v_max3_f32 v18, v18, v19, s0
	v_div_scale_f32 v19, s[0:1], v18, v18, s10
	v_rcp_f32_e32 v20, v19
	s_mov_b32 s1, 0xc0c00000
	s_or_b32 s0, s2, s3
	s_bitcmp0_b32 s15, 14
	v_fma_f32 v21, -v19, v20, 1.0
	v_fmac_f32_e32 v20, v21, v20
	v_div_scale_f32 v21, vcc, s10, v18, s10
	v_mul_f32_e32 v22, v21, v20
	v_fma_f32 v23, -v19, v22, v21
	v_fmac_f32_e32 v22, v23, v20
	v_fma_f32 v19, -v19, v22, v21
	v_div_fmas_f32 v19, v19, v20, v22
	v_div_fixup_f32 v19, v19, v18, s10
	v_mul_f32_e32 v14, v14, v19
	v_mov_b32_e32 v22, 0x40c00000
	v_med3_f32 v21, v14, s1, v22
	v_mul_f32_e32 v14, v15, v19
	v_med3_f32 v15, v14, s1, v22
	v_mov_b32_e32 v20, 0
	v_mul_f32_e32 v6, v6, v19
	v_mul_f32_e32 v7, v7, v19
	v_cvt_scalef32_pk_fp4_f32 v20, v21, v15, 1.0
	v_med3_f32 v6, v6, s1, v22
	v_med3_f32 v7, v7, s1, v22
	v_mov_b32_e32 v21, 0
	v_mul_f32_e32 v15, v16, v19
	v_mul_f32_e32 v16, v17, v19
	v_cvt_scalef32_pk_fp4_f32 v21, v6, v7, 1.0
	v_mul_f32_e32 v6, v8, v19
	v_mul_f32_e32 v7, v9, v19
	v_med3_f32 v15, v15, s1, v22
	v_med3_f32 v16, v16, s1, v22
	v_mul_f32_e32 v10, v10, v19
	v_mul_f32_e32 v11, v11, v19
	v_med3_f32 v6, v6, s1, v22
	v_med3_f32 v7, v7, s1, v22
	v_mul_f32_e32 v2, v2, v19
	v_mul_f32_e32 v3, v3, v19
	v_cvt_scalef32_pk_fp4_f32 v20, v15, v16, 1.0 op_sel:[0,0,1,0]
	v_med3_f32 v10, v10, s1, v22
	v_med3_f32 v11, v11, s1, v22
	v_cvt_scalef32_pk_fp4_f32 v21, v6, v7, 1.0 op_sel:[0,0,1,0]
	v_med3_f32 v2, v2, s1, v22
	v_med3_f32 v3, v3, s1, v22
	s_cselect_b64 s[8:9], -1, 0
	v_cvt_scalef32_pk_fp4_f32 v20, v10, v11, 1.0 op_sel:[0,0,0,1]
	v_mul_f32_e32 v10, v12, v19
	v_mul_f32_e32 v11, v13, v19
	v_cvt_scalef32_pk_fp4_f32 v21, v2, v3, 1.0 op_sel:[0,0,0,1]
	v_mul_f32_e32 v2, v4, v19
	v_mul_f32_e32 v3, v5, v19
	v_med3_f32 v10, v10, s1, v22
	v_med3_f32 v11, v11, s1, v22
	v_med3_f32 v2, v2, s1, v22
	v_med3_f32 v3, v3, s1, v22
	s_brev_b32 s1, 64
	s_and_b64 s[2:3], s[8:9], exec
	s_cselect_b32 s1, s1, 0x4000000
	s_add_u32 s10, s82, s1
	s_addc_u32 s11, s83, 0
	s_ashr_i32 s1, s0, 31
	s_lshl_b64 s[2:3], s[0:1], 9
	s_add_u32 s2, s10, s2
	v_mov_b32_e32 v14, 0
	v_cvt_scalef32_pk_fp4_f32 v20, v10, v11, 1.0 op_sel:[0,0,1,1]
	v_cvt_scalef32_pk_fp4_f32 v21, v2, v3, 1.0 op_sel:[0,0,1,1]
	s_addc_u32 s3, s11, s3
	global_store_dwordx2 v1, v[20:21], s[2:3]
	s_and_saveexec_b64 s[2:3], s[4:5]
	s_cbranch_execz .LBB0_728
	s_mov_b32 s10, 0x1d00000
	s_and_b64 s[4:5], s[8:9], exec
	s_cselect_b32 s4, s10, 0x1d00004
	s_add_u32 s4, s82, s4
	s_addc_u32 s5, s83, 0
	s_lshl_b64 s[0:1], s[0:1], 3
	s_add_u32 s0, s4, s0
	v_mul_f32_e32 v1, 0x3e124925, v18
	s_addc_u32 s1, s5, s1
	global_store_dword v14, v1, s[0:1]

; #define GAS __attribute__((address_space(1)))
; #define Q4(x) fminf(fmaxf((x) * sc, -6.f), 6.f)
; #define Q4(x) fminf(fmaxf((x) * sc, -6.f), 6.f)
; __device__ __forceinline__ void table_row_to_fp4(const f32x4 (&v)[4], int lane, bool isv, int r, unsigned char* ws) {
;     float m = 0.f;
; #pragma unroll
;     for (int j = 0; j < 4; ++j) m = fmaxf(fmaxf(m, fmaxf(fabsf(v[j].x), fabsf(v[j].y))), fmaxf(fabsf(v[j].z), fabsf(v[j].w)));
; #pragma unroll
;     for (int o = 1; o < 64; o <<= 1) m = fmaxf(m, __shfl_xor(m, o));
;     m = fmaxf(m, 1e-30f);
;     const float sc = 7.f / m;
;     unsigned w0 = 0u, w1 = 0u;
;     ...
;     w0 = __builtin_amdgcn_cvt_scalef32_pk_fp4_f32(w0, Q4(v[0].x), Q4(v[0].y), 1.0f, 0); w0 = __builtin_amdgcn_cvt_scalef32_pk_fp4_f32(w0, Q4(v[0].z), Q4(v[0].w), 1.0f, 1);
;     w0 = __builtin_amdgcn_cvt_scalef32_pk_fp4_f32(w0, Q4(v[1].x), Q4(v[1].y), 1.0f, 2); w0 = __builtin_amdgcn_cvt_scalef32_pk_fp4_f32(w0, Q4(v[1].z), Q4(v[1].w), 1.0f, 3);
;     w1 = __builtin_amdgcn_cvt_scalef32_pk_fp4_f32(w1, Q4(v[2].x), Q4(v[2].y), 1.0f, 0); w1 = __builtin_amdgcn_cvt_scalef32_pk_fp4_f32(w1, Q4(v[2].z), Q4(v[2].w), 1.0f, 1);
;     w1 = __builtin_amdgcn_cvt_scalef32_pk_fp4_f32(w1, Q4(v[3].x), Q4(v[3].y), 1.0f, 2); w1 = __builtin_amdgcn_cvt_scalef32_pk_fp4_f32(w1, Q4(v[3].z), Q4(v[3].w), 1.0f, 3);
;     ...
;     *((GAS v2u*)(ws + (isv ? WS_V8 : WS_U8) + (size_t)r * 512) + lane) = (v2u){w0, w1};
;     if (lane == 0) ((float*)(ws + (isv ? WS_DQV : WS_DQU)))[r] = m * (1.f / 7.f);
; __device__ __forceinline__ void barrier_side_convert(int k, const float* U, const float* V, unsigned char* ws) {
;     ...
;         if (j < RB && g0 + j < glim) { const int g = g0 + j, tb = g >> 14, r = NEXP * (tb >> 1) + (g & (NEXP - 1)); const GAS f32x4* src = (const GAS f32x4*)(((tb & 1) ? V : U) + (size_t)r * D) + 4 * lane;
; #pragma unroll
;             for (int q = 0; q < 4; ++q) v[jj][q] = src[q]; } }
; #pragma unroll
;     for (int jj = 0; jj < 3; ++jj) { const int j = wave - 1 + 7 * jj;
;         if (j < RB && g0 + j < glim) { const int g = g0 + j, tb = g >> 14, r = NEXP * (tb >> 1) + (g & (NEXP - 1)); table_row_to_fp4(v[jj], lane, (tb & 1) != 0, r, ws); } }
.LBB0_911:
	s_andn2_b64 vcc, exec, s[4:5]
	v_cmp_eq_u32_e64 s[4:5], 0, v1
	s_cbranch_vccnz .LBB0_916
	s_add_i32 s2, s2, s14
	s_cmp_gt_i32 s2, 0xffff
	s_cbranch_scc1 .LBB0_916
	s_waitcnt vmcnt(0)
	v_max_f32_e64 v50, |v47|, |v47|
	v_max_f32_e64 v51, |v46|, |v46|
	v_max_f32_e32 v50, v51, v50
	v_max_f32_e64 v51, |v49|, |v49|
	v_max_f32_e64 v52, |v48|, |v48|
	v_max_f32_e32 v51, v52, v51
	v_max3_f32 v50, v50, 0, v51
	v_max_f32_e64 v51, |v43|, |v43|
	v_max_f32_e64 v52, |v42|, |v42|
	v_max_f32_e32 v51, v52, v51
	v_max_f32_e64 v52, |v45|, |v45|
	v_max_f32_e64 v53, |v44|, |v44|
	v_max_f32_e32 v52, v53, v52
	v_max3_f32 v50, v50, v51, v52
	v_max_f32_e64 v51, |v39|, |v39|
	v_max_f32_e64 v52, |v38|, |v38|
	v_max_f32_e32 v51, v52, v51
	v_max_f32_e64 v52, |v41|, |v41|
	v_max_f32_e64 v53, |v40|, |v40|
	v_max_f32_e32 v52, v53, v52
	v_max3_f32 v50, v50, v51, v52
	v_max_f32_e64 v51, |v35|, |v35|
	v_max_f32_e64 v52, |v34|, |v34|
	v_max_f32_e32 v51, v52, v51
	v_max_f32_e64 v52, |v37|, |v37|
	v_max_f32_e64 v53, |v36|, |v36|
	v_max_f32_e32 v52, v53, v52
	v_max3_f32 v50, v50, v51, v52
	v_mbcnt_lo_u32_b32 v51, -1, 0
	v_mbcnt_hi_u32_b32 v51, -1, v51
	v_and_b32_e32 v52, 64, v51
	v_add_u32_e32 v52, 64, v52
	v_xor_b32_e32 v53, 1, v51
	v_cmp_lt_i32_e32 vcc, v53, v52
	s_mov_b32 s10, 0xda24260
	s_mov_b32 s17, 0x40e00000
	v_cndmask_b32_e32 v53, v51, v53, vcc
	v_lshlrev_b32_e32 v53, 2, v53
	ds_bpermute_b32 v53, v53, v50
	s_ashr_i32 s3, s2, 1
	s_and_b32 s3, s3, 0xffffc000
	s_and_b32 s12, s2, 0x3fff
	s_waitcnt lgkmcnt(0)
	v_max_f32_e32 v53, v53, v53
	v_max_f32_e32 v50, v50, v53
	v_xor_b32_e32 v53, 2, v51
	v_cmp_lt_i32_e32 vcc, v53, v52
	s_nop 1
	v_cndmask_b32_e32 v53, v51, v53, vcc
	v_lshlrev_b32_e32 v53, 2, v53
	ds_bpermute_b32 v53, v53, v50
	s_waitcnt lgkmcnt(0)
	v_max_f32_e32 v53, v53, v53
	v_max_f32_e32 v50, v50, v53
	v_xor_b32_e32 v53, 4, v51
	v_cmp_lt_i32_e32 vcc, v53, v52
	s_nop 1
	v_cndmask_b32_e32 v53, v51, v53, vcc
	v_lshlrev_b32_e32 v53, 2, v53
	ds_bpermute_b32 v53, v53, v50
	s_waitcnt lgkmcnt(0)
	v_max_f32_e32 v53, v53, v53
	v_max_f32_e32 v50, v50, v53
	v_xor_b32_e32 v53, 8, v51
	v_cmp_lt_i32_e32 vcc, v53, v52
	s_nop 1
	v_cndmask_b32_e32 v53, v51, v53, vcc
	v_lshlrev_b32_e32 v53, 2, v53
	ds_bpermute_b32 v53, v53, v50
	s_waitcnt lgkmcnt(0)
	v_max_f32_e32 v53, v53, v53
	v_max_f32_e32 v50, v50, v53
	v_xor_b32_e32 v53, 16, v51
	v_cmp_lt_i32_e32 vcc, v53, v52
	s_nop 1
	v_cndmask_b32_e32 v53, v51, v53, vcc
	v_lshlrev_b32_e32 v53, 2, v53
	ds_bpermute_b32 v53, v53, v50
	s_waitcnt lgkmcnt(0)
	v_max_f32_e32 v53, v53, v53
	v_max_f32_e32 v50, v50, v53
	v_xor_b32_e32 v53, 32, v51
	v_cmp_lt_i32_e32 vcc, v53, v52
	s_nop 1
	v_cndmask_b32_e32 v51, v51, v53, vcc
	v_lshlrev_b32_e32 v51, 2, v51
	ds_bpermute_b32 v51, v51, v50
	s_waitcnt lgkmcnt(0)
	v_max3_f32 v50, v50, v51, s10
	v_div_scale_f32 v51, s[10:11], v50, v50, s17
	v_rcp_f32_e32 v52, v51
	s_or_b32 s10, s3, s12
	s_bitcmp0_b32 s2, 14
	s_mov_b32 s2, 0xc0c00000
	v_fma_f32 v53, -v51, v52, 1.0
	v_fmac_f32_e32 v52, v53, v52
	v_div_scale_f32 v53, vcc, s17, v50, s17
	v_mul_f32_e32 v54, v53, v52
	v_fma_f32 v55, -v51, v54, v53
	v_fmac_f32_e32 v54, v55, v52
	v_fma_f32 v51, -v51, v54, v53
	v_div_fmas_f32 v51, v51, v52, v54
	v_div_fixup_f32 v51, v51, v50, s17
	v_mul_f32_e32 v46, v46, v51
	v_mov_b32_e32 v54, 0x40c00000
	v_med3_f32 v53, v46, s2, v54
	v_mul_f32_e32 v46, v47, v51
	v_med3_f32 v47, v46, s2, v54
	v_mov_b32_e32 v52, 0
	v_mul_f32_e32 v38, v38, v51
	v_mul_f32_e32 v39, v39, v51
	v_cvt_scalef32_pk_fp4_f32 v52, v53, v47, 1.0
	v_med3_f32 v38, v38, s2, v54
	v_med3_f32 v39, v39, s2, v54
	v_mov_b32_e32 v53, 0
	v_mul_f32_e32 v47, v48, v51
	v_mul_f32_e32 v48, v49, v51
	v_cvt_scalef32_pk_fp4_f32 v53, v38, v39, 1.0
	v_mul_f32_e32 v38, v40, v51
	v_mul_f32_e32 v39, v41, v51
	v_med3_f32 v47, v47, s2, v54
	v_med3_f32 v48, v48, s2, v54
	v_mul_f32_e32 v42, v42, v51
	v_mul_f32_e32 v43, v43, v51
	v_med3_f32 v38, v38, s2, v54
	v_med3_f32 v39, v39, s2, v54
	v_mul_f32_e32 v34, v34, v51
	v_mul_f32_e32 v35, v35, v51
	v_cvt_scalef32_pk_fp4_f32 v52, v47, v48, 1.0 op_sel:[0,0,1,0]
	v_med3_f32 v42, v42, s2, v54
	v_med3_f32 v43, v43, s2, v54
	v_cvt_scalef32_pk_fp4_f32 v53, v38, v39, 1.0 op_sel:[0,0,1,0]
	v_med3_f32 v34, v34, s2, v54
	v_med3_f32 v35, v35, s2, v54
	s_cselect_b64 s[12:13], -1, 0
	v_cvt_scalef32_pk_fp4_f32 v52, v42, v43, 1.0 op_sel:[0,0,0,1]
	v_mul_f32_e32 v42, v44, v51
	v_mul_f32_e32 v43, v45, v51
	v_cvt_scalef32_pk_fp4_f32 v53, v34, v35, 1.0 op_sel:[0,0,0,1]
	v_mul_f32_e32 v34, v36, v51
	v_mul_f32_e32 v35, v37, v51
	v_med3_f32 v42, v42, s2, v54
	v_med3_f32 v43, v43, s2, v54
	v_med3_f32 v34, v34, s2, v54
	v_med3_f32 v35, v35, s2, v54
	s_brev_b32 s11, 64
	s_and_b64 s[2:3], s[12:13], exec
	s_cselect_b32 s2, s11, 0x4000000
	s_add_u32 s17, s82, s2
	s_addc_u32 s18, s83, 0
	s_ashr_i32 s11, s10, 31
	s_lshl_b64 s[2:3], s[10:11], 9
	s_add_u32 s2, s17, s2
	v_mov_b32_e32 v46, 0
	v_cvt_scalef32_pk_fp4_f32 v52, v42, v43, 1.0 op_sel:[0,0,1,1]
	v_cvt_scalef32_pk_fp4_f32 v53, v34, v35, 1.0 op_sel:[0,0,1,1]
	s_addc_u32 s3, s18, s3
	v_lshlrev_b32_e32 v34, 3, v1
	global_store_dwordx2 v34, v[52:53], s[2:3]
	s_and_saveexec_b64 s[2:3], s[4:5]
	s_cbranch_execz .LBB0_915
	s_mov_b32 s17, 0x1d00000
	s_and_b64 s[12:13], s[12:13], exec
	s_cselect_b32 s12, s17, 0x1d00004
	s_add_u32 s12, s82, s12
	s_addc_u32 s13, s83, 0
	s_lshl_b64 s[10:11], s[10:11], 3
	s_add_u32 s10, s12, s10
	v_mul_f32_e32 v34, 0x3e124925, v50
	s_addc_u32 s11, s13, s11
	global_store_dword v46, v34, s[10:11]

; #define GAS __attribute__((address_space(1)))
; #define Q4(x) fminf(fmaxf((x) * sc, -6.f), 6.f)
; #define Q4(x) fminf(fmaxf((x) * sc, -6.f), 6.f)
; __device__ __forceinline__ void table_row_to_fp4(const f32x4 (&v)[4], int lane, bool isv, int r, unsigned char* ws) {
;     float m = 0.f;
; #pragma unroll
;     for (int j = 0; j < 4; ++j) m = fmaxf(fmaxf(m, fmaxf(fabsf(v[j].x), fabsf(v[j].y))), fmaxf(fabsf(v[j].z), fabsf(v[j].w)));
; #pragma unroll
;     for (int o = 1; o < 64; o <<= 1) m = fmaxf(m, __shfl_xor(m, o));
;     m = fmaxf(m, 1e-30f);
;     const float sc = 7.f / m;
;     unsigned w0 = 0u, w1 = 0u;
;     ...
;     w0 = __builtin_amdgcn_cvt_scalef32_pk_fp4_f32(w0, Q4(v[0].x), Q4(v[0].y), 1.0f, 0); w0 = __builtin_amdgcn_cvt_scalef32_pk_fp4_f32(w0, Q4(v[0].z), Q4(v[0].w), 1.0f, 1);
;     w0 = __builtin_amdgcn_cvt_scalef32_pk_fp4_f32(w0, Q4(v[1].x), Q4(v[1].y), 1.0f, 2); w0 = __builtin_amdgcn_cvt_scalef32_pk_fp4_f32(w0, Q4(v[1].z), Q4(v[1].w), 1.0f, 3);
;     w1 = __builtin_amdgcn_cvt_scalef32_pk_fp4_f32(w1, Q4(v[2].x), Q4(v[2].y), 1.0f, 0); w1 = __builtin_amdgcn_cvt_scalef32_pk_fp4_f32(w1, Q4(v[2].z), Q4(v[2].w), 1.0f, 1);
;     w1 = __builtin_amdgcn_cvt_scalef32_pk_fp4_f32(w1, Q4(v[3].x), Q4(v[3].y), 1.0f, 2); w1 = __builtin_amdgcn_cvt_scalef32_pk_fp4_f32(w1, Q4(v[3].z), Q4(v[3].w), 1.0f, 3);
;     ...
;     *((GAS v2u*)(ws + (isv ? WS_V8 : WS_U8) + (size_t)r * 512) + lane) = (v2u){w0, w1};
;     if (lane == 0) ((float*)(ws + (isv ? WS_DQV : WS_DQU)))[r] = m * (1.f / 7.f);
; __device__ __forceinline__ void barrier_side_convert(int k, const float* U, const float* V, unsigned char* ws) {
;     ...
;         if (j < RB && g0 + j < glim) { const int g = g0 + j, tb = g >> 14, r = NEXP * (tb >> 1) + (g & (NEXP - 1)); const GAS f32x4* src = (const GAS f32x4*)(((tb & 1) ? V : U) + (size_t)r * D) + 4 * lane;
; #pragma unroll
;             for (int q = 0; q < 4; ++q) v[jj][q] = src[q]; } }
; #pragma unroll
;     for (int jj = 0; jj < 3; ++jj) { const int j = wave - 1 + 7 * jj;
;         if (j < RB && g0 + j < glim) { const int g = g0 + j, tb = g >> 14, r = NEXP * (tb >> 1) + (g & (NEXP - 1)); table_row_to_fp4(v[jj], lane, (tb & 1) != 0, r, ws); } }
.LBB0_916:
	s_andn2_b64 vcc, exec, s[8:9]
	s_cbranch_vccnz .LBB0_921
	s_add_i32 s16, s16, s14
	s_cmp_gt_i32 s16, 0xffff
	s_cbranch_scc1 .LBB0_921
	s_waitcnt vmcnt(0)
	v_max_f32_e64 v34, |v31|, |v31|
	v_max_f32_e64 v35, |v30|, |v30|
	v_max_f32_e32 v34, v35, v34
	v_max_f32_e64 v35, |v33|, |v33|
	v_max_f32_e64 v36, |v32|, |v32|
	v_max_f32_e32 v35, v36, v35
	v_max3_f32 v34, v34, 0, v35
	v_max_f32_e64 v35, |v27|, |v27|
	v_max_f32_e64 v36, |v26|, |v26|
	v_max_f32_e32 v35, v36, v35
	v_max_f32_e64 v36, |v29|, |v29|
	v_max_f32_e64 v37, |v28|, |v28|
	v_max_f32_e32 v36, v37, v36
	v_max3_f32 v34, v34, v35, v36
	v_max_f32_e64 v35, |v23|, |v23|
	v_max_f32_e64 v36, |v22|, |v22|
	v_max_f32_e32 v35, v36, v35
	v_max_f32_e64 v36, |v25|, |v25|
	v_max_f32_e64 v37, |v24|, |v24|
	v_max_f32_e32 v36, v37, v36
	v_max3_f32 v34, v34, v35, v36
	v_max_f32_e64 v35, |v19|, |v19|
	v_max_f32_e64 v36, |v18|, |v18|
	v_max_f32_e32 v35, v36, v35
	v_max_f32_e64 v36, |v21|, |v21|
	v_max_f32_e64 v37, |v20|, |v20|
	v_max_f32_e32 v36, v37, v36
	v_max3_f32 v34, v34, v35, v36
	v_mbcnt_lo_u32_b32 v35, -1, 0
	v_mbcnt_hi_u32_b32 v35, -1, v35
	v_and_b32_e32 v36, 64, v35
	v_add_u32_e32 v36, 64, v36
	v_xor_b32_e32 v37, 1, v35
	v_cmp_lt_i32_e32 vcc, v37, v36
	s_ashr_i32 s2, s16, 1
	s_and_b32 s8, s2, 0xffffc000
	v_cndmask_b32_e32 v37, v35, v37, vcc
	v_lshlrev_b32_e32 v37, 2, v37
	ds_bpermute_b32 v37, v37, v34
	s_mov_b32 s2, 0xda24260
	s_mov_b32 s12, 0x40e00000
	s_and_b32 s9, s16, 0x3fff
	s_or_b32 s8, s8, s9
	s_waitcnt lgkmcnt(0)
	v_max_f32_e32 v37, v37, v37
	v_max_f32_e32 v34, v34, v37
	v_xor_b32_e32 v37, 2, v35
	v_cmp_lt_i32_e32 vcc, v37, v36
	s_bitcmp0_b32 s16, 14
	s_cselect_b64 s[10:11], -1, 0
	v_cndmask_b32_e32 v37, v35, v37, vcc
	v_lshlrev_b32_e32 v37, 2, v37
	ds_bpermute_b32 v37, v37, v34
	s_brev_b32 s9, 64
	s_waitcnt lgkmcnt(0)
	v_max_f32_e32 v37, v37, v37
	v_max_f32_e32 v34, v34, v37
	v_xor_b32_e32 v37, 4, v35
	v_cmp_lt_i32_e32 vcc, v37, v36
	s_nop 1
	v_cndmask_b32_e32 v37, v35, v37, vcc
	v_lshlrev_b32_e32 v37, 2, v37
	ds_bpermute_b32 v37, v37, v34
	s_waitcnt lgkmcnt(0)
	v_max_f32_e32 v37, v37, v37
	v_max_f32_e32 v34, v34, v37
	v_xor_b32_e32 v37, 8, v35
	v_cmp_lt_i32_e32 vcc, v37, v36
	s_nop 1
	v_cndmask_b32_e32 v37, v35, v37, vcc
	v_lshlrev_b32_e32 v37, 2, v37
	ds_bpermute_b32 v37, v37, v34
	s_waitcnt lgkmcnt(0)
	v_max_f32_e32 v37, v37, v37
	v_max_f32_e32 v34, v34, v37
	v_xor_b32_e32 v37, 16, v35
	v_cmp_lt_i32_e32 vcc, v37, v36
	s_nop 1
	v_cndmask_b32_e32 v37, v35, v37, vcc
	v_lshlrev_b32_e32 v37, 2, v37
	ds_bpermute_b32 v37, v37, v34
	s_waitcnt lgkmcnt(0)
	v_max_f32_e32 v37, v37, v37
	v_max_f32_e32 v34, v34, v37
	v_xor_b32_e32 v37, 32, v35
	v_cmp_lt_i32_e32 vcc, v37, v36
	s_nop 1
	v_cndmask_b32_e32 v35, v35, v37, vcc
	v_lshlrev_b32_e32 v35, 2, v35
	ds_bpermute_b32 v35, v35, v34
	s_waitcnt lgkmcnt(0)
	v_max3_f32 v34, v34, v35, s2
	v_div_scale_f32 v35, s[2:3], v34, v34, s12
	v_rcp_f32_e32 v36, v35
	s_mov_b32 s2, 0xc0c00000
	v_fma_f32 v37, -v35, v36, 1.0
	v_fmac_f32_e32 v36, v37, v36
	v_div_scale_f32 v37, vcc, s12, v34, s12
	v_mul_f32_e32 v38, v37, v36
	v_fma_f32 v39, -v35, v38, v37
	v_fmac_f32_e32 v38, v39, v36
	v_fma_f32 v35, -v35, v38, v37
	v_div_fmas_f32 v35, v35, v36, v38
	v_div_fixup_f32 v35, v35, v34, s12
	v_mul_f32_e32 v30, v30, v35
	v_mov_b32_e32 v38, 0x40c00000
	v_med3_f32 v37, v30, s2, v38
	v_mul_f32_e32 v30, v31, v35
	v_med3_f32 v31, v30, s2, v38
	v_mov_b32_e32 v36, 0
	v_mul_f32_e32 v22, v22, v35
	v_mul_f32_e32 v23, v23, v35
	v_cvt_scalef32_pk_fp4_f32 v36, v37, v31, 1.0
	v_med3_f32 v22, v22, s2, v38
	v_med3_f32 v23, v23, s2, v38
	v_mov_b32_e32 v37, 0
	v_mul_f32_e32 v31, v32, v35
	v_mul_f32_e32 v32, v33, v35
	v_cvt_scalef32_pk_fp4_f32 v37, v22, v23, 1.0
	v_mul_f32_e32 v22, v24, v35
	v_mul_f32_e32 v23, v25, v35
	v_med3_f32 v31, v31, s2, v38
	v_med3_f32 v32, v32, s2, v38
	v_mul_f32_e32 v26, v26, v35
	v_mul_f32_e32 v27, v27, v35
	v_med3_f32 v22, v22, s2, v38
	v_med3_f32 v23, v23, s2, v38
	v_mul_f32_e32 v18, v18, v35
	v_mul_f32_e32 v19, v19, v35
	v_cvt_scalef32_pk_fp4_f32 v36, v31, v32, 1.0 op_sel:[0,0,1,0]
	v_med3_f32 v26, v26, s2, v38
	v_med3_f32 v27, v27, s2, v38
	v_cvt_scalef32_pk_fp4_f32 v37, v22, v23, 1.0 op_sel:[0,0,1,0]
	v_med3_f32 v18, v18, s2, v38
	v_med3_f32 v19, v19, s2, v38
	v_cvt_scalef32_pk_fp4_f32 v36, v26, v27, 1.0 op_sel:[0,0,0,1]
	v_mul_f32_e32 v26, v28, v35
	v_mul_f32_e32 v27, v29, v35
	v_cvt_scalef32_pk_fp4_f32 v37, v18, v19, 1.0 op_sel:[0,0,0,1]
	v_mul_f32_e32 v18, v20, v35
	v_mul_f32_e32 v19, v21, v35
	v_med3_f32 v26, v26, s2, v38
	v_med3_f32 v27, v27, s2, v38
	v_med3_f32 v18, v18, s2, v38
	v_med3_f32 v19, v19, s2, v38
	s_and_b64 s[2:3], s[10:11], exec
	s_cselect_b32 s2, s9, 0x4000000
	s_add_u32 s12, s82, s2
	s_addc_u32 s13, s83, 0
	s_ashr_i32 s9, s8, 31
	s_lshl_b64 s[2:3], s[8:9], 9
	s_add_u32 s2, s12, s2
	v_mov_b32_e32 v30, 0
	v_cvt_scalef32_pk_fp4_f32 v36, v26, v27, 1.0 op_sel:[0,0,1,1]
	v_cvt_scalef32_pk_fp4_f32 v37, v18, v19, 1.0 op_sel:[0,0,1,1]
	s_addc_u32 s3, s13, s3
	v_lshlrev_b32_e32 v18, 3, v1
	global_store_dwordx2 v18, v[36:37], s[2:3]
	s_and_saveexec_b64 s[2:3], s[4:5]
	s_cbranch_execz .LBB0_920
	s_mov_b32 s12, 0x1d00000
	s_and_b64 s[10:11], s[10:11], exec
	s_cselect_b32 s10, s12, 0x1d00004
	s_add_u32 s10, s82, s10
	s_addc_u32 s11, s83, 0
	s_lshl_b64 s[8:9], s[8:9], 3
	s_add_u32 s8, s10, s8
	v_mul_f32_e32 v18, 0x3e124925, v34
	s_addc_u32 s9, s11, s9
	global_store_dword v30, v18, s[8:9]

; #define GAS __attribute__((address_space(1)))
; #define Q4(x) fminf(fmaxf((x) * sc, -6.f), 6.f)
; #define Q4(x) fminf(fmaxf((x) * sc, -6.f), 6.f)
; __device__ __forceinline__ void table_row_to_fp4(const f32x4 (&v)[4], int lane, bool isv, int r, unsigned char* ws) {
;     float m = 0.f;
; #pragma unroll
;     for (int j = 0; j < 4; ++j) m = fmaxf(fmaxf(m, fmaxf(fabsf(v[j].x), fabsf(v[j].y))), fmaxf(fabsf(v[j].z), fabsf(v[j].w)));
; #pragma unroll
;     for (int o = 1; o < 64; o <<= 1) m = fmaxf(m, __shfl_xor(m, o));
;     m = fmaxf(m, 1e-30f);
;     const float sc = 7.f / m;
;     unsigned w0 = 0u, w1 = 0u;
;     ...
;     w0 = __builtin_amdgcn_cvt_scalef32_pk_fp4_f32(w0, Q4(v[0].x), Q4(v[0].y), 1.0f, 0); w0 = __builtin_amdgcn_cvt_scalef32_pk_fp4_f32(w0, Q4(v[0].z), Q4(v[0].w), 1.0f, 1);
;     w0 = __builtin_amdgcn_cvt_scalef32_pk_fp4_f32(w0, Q4(v[1].x), Q4(v[1].y), 1.0f, 2); w0 = __builtin_amdgcn_cvt_scalef32_pk_fp4_f32(w0, Q4(v[1].z), Q4(v[1].w), 1.0f, 3);
;     w1 = __builtin_amdgcn_cvt_scalef32_pk_fp4_f32(w1, Q4(v[2].x), Q4(v[2].y), 1.0f, 0); w1 = __builtin_amdgcn_cvt_scalef32_pk_fp4_f32(w1, Q4(v[2].z), Q4(v[2].w), 1.0f, 1);
;     w1 = __builtin_amdgcn_cvt_scalef32_pk_fp4_f32(w1, Q4(v[3].x), Q4(v[3].y), 1.0f, 2); w1 = __builtin_amdgcn_cvt_scalef32_pk_fp4_f32(w1, Q4(v[3].z), Q4(v[3].w), 1.0f, 3);
;     ...
;     *((GAS v2u*)(ws + (isv ? WS_V8 : WS_U8) + (size_t)r * 512) + lane) = (v2u){w0, w1};
;     if (lane == 0) ((float*)(ws + (isv ? WS_DQV : WS_DQU)))[r] = m * (1.f / 7.f);
; __device__ __forceinline__ void barrier_side_convert(int k, const float* U, const float* V, unsigned char* ws) {
;     ...
;         if (j < RB && g0 + j < glim) { const int g = g0 + j, tb = g >> 14, r = NEXP * (tb >> 1) + (g & (NEXP - 1)); const GAS f32x4* src = (const GAS f32x4*)(((tb & 1) ? V : U) + (size_t)r * D) + 4 * lane;
; #pragma unroll
;             for (int q = 0; q < 4; ++q) v[jj][q] = src[q]; } }
; #pragma unroll
;     for (int jj = 0; jj < 3; ++jj) { const int j = wave - 1 + 7 * jj;
;         if (j < RB && g0 + j < glim) { const int g = g0 + j, tb = g >> 14, r = NEXP * (tb >> 1) + (g & (NEXP - 1)); table_row_to_fp4(v[jj], lane, (tb & 1) != 0, r, ws); } }
.LBB0_921:
	s_andn2_b64 vcc, exec, s[0:1]
	s_cbranch_vccnz .LBB0_926
	s_add_i32 s15, s15, s14
	s_cmp_gt_i32 s15, 0xffff
	s_cbranch_scc1 .LBB0_926
	s_waitcnt vmcnt(0)
	v_max_f32_e64 v18, |v15|, |v15|
	v_max_f32_e64 v19, |v14|, |v14|
	v_max_f32_e32 v18, v19, v18
	v_max_f32_e64 v19, |v17|, |v17|
	v_max_f32_e64 v20, |v16|, |v16|
	v_max_f32_e32 v19, v20, v19
	v_max3_f32 v18, v18, 0, v19
	v_max_f32_e64 v19, |v11|, |v11|
	v_max_f32_e64 v20, |v10|, |v10|
	v_max_f32_e32 v19, v20, v19
	v_max_f32_e64 v20, |v13|, |v13|
	v_max_f32_e64 v21, |v12|, |v12|
	v_max_f32_e32 v20, v21, v20
	v_max3_f32 v18, v18, v19, v20
	v_max_f32_e64 v19, |v7|, |v7|
	v_max_f32_e64 v20, |v6|, |v6|
	v_max_f32_e32 v19, v20, v19
	v_max_f32_e64 v20, |v9|, |v9|
	v_max_f32_e64 v21, |v8|, |v8|
	v_max_f32_e32 v20, v21, v20
	v_max3_f32 v18, v18, v19, v20
	v_max_f32_e64 v19, |v3|, |v3|
	v_max_f32_e64 v20, |v2|, |v2|
	v_max_f32_e32 v19, v20, v19
	v_max_f32_e64 v20, |v5|, |v5|
	v_max_f32_e64 v21, |v4|, |v4|
	v_max_f32_e32 v20, v21, v20
	v_max3_f32 v18, v18, v19, v20
	v_mbcnt_lo_u32_b32 v19, -1, 0
	v_mbcnt_hi_u32_b32 v19, -1, v19
	v_and_b32_e32 v20, 64, v19
	v_add_u32_e32 v20, 64, v20
	v_xor_b32_e32 v21, 1, v19
	v_cmp_lt_i32_e32 vcc, v21, v20
	s_ashr_i32 s0, s15, 1
	s_and_b32 s2, s0, 0xffffc000
	v_cndmask_b32_e32 v21, v19, v21, vcc
	v_lshlrev_b32_e32 v21, 2, v21
	ds_bpermute_b32 v21, v21, v18
	s_mov_b32 s0, 0xda24260
	s_mov_b32 s10, 0x40e00000
	s_and_b32 s3, s15, 0x3fff
	v_lshlrev_b32_e32 v1, 3, v1
	s_waitcnt lgkmcnt(0)
	v_max_f32_e32 v21, v21, v21
	v_max_f32_e32 v18, v18, v21
	v_xor_b32_e32 v21, 2, v19
	v_cmp_lt_i32_e32 vcc, v21, v20
	s_nop 1
	v_cndmask_b32_e32 v21, v19, v21, vcc
	v_lshlrev_b32_e32 v21, 2, v21
	ds_bpermute_b32 v21, v21, v18
	s_waitcnt lgkmcnt(0)
	v_max_f32_e32 v21, v21, v21
	v_max_f32_e32 v18, v18, v21
	v_xor_b32_e32 v21, 4, v19
	v_cmp_lt_i32_e32 vcc, v21, v20
	s_nop 1
	v_cndmask_b32_e32 v21, v19, v21, vcc
	v_lshlrev_b32_e32 v21, 2, v21
	ds_bpermute_b32 v21, v21, v18
	s_waitcnt lgkmcnt(0)
	v_max_f32_e32 v21, v21, v21
	v_max_f32_e32 v18, v18, v21
	v_xor_b32_e32 v21, 8, v19
	v_cmp_lt_i32_e32 vcc, v21, v20
	s_nop 1
	v_cndmask_b32_e32 v21, v19, v21, vcc
	v_lshlrev_b32_e32 v21, 2, v21
	ds_bpermute_b32 v21, v21, v18
	s_waitcnt lgkmcnt(0)
	v_max_f32_e32 v21, v21, v21
	v_max_f32_e32 v18, v18, v21
	v_xor_b32_e32 v21, 16, v19
	v_cmp_lt_i32_e32 vcc, v21, v20
	s_nop 1
	v_cndmask_b32_e32 v21, v19, v21, vcc
	v_lshlrev_b32_e32 v21, 2, v21
	ds_bpermute_b32 v21, v21, v18
	s_waitcnt lgkmcnt(0)
	v_max_f32_e32 v21, v21, v21
	v_max_f32_e32 v18, v18, v21
	v_xor_b32_e32 v21, 32, v19
	v_cmp_lt_i32_e32 vcc, v21, v20
	s_nop 1
	v_cndmask_b32_e32 v19, v19, v21, vcc
	v_lshlrev_b32_e32 v19, 2, v19
	ds_bpermute_b32 v19, v19, v18
	s_waitcnt lgkmcnt(0)
	v_max3_f32 v18, v18, v19, s0
	v_div_scale_f32 v19, s[0:1], v18, v18, s10
	v_rcp_f32_e32 v20, v19
	s_mov_b32 s1, 0xc0c00000
	s_or_b32 s0, s2, s3
	s_bitcmp0_b32 s15, 14
	v_fma_f32 v21, -v19, v20, 1.0
	v_fmac_f32_e32 v20, v21, v20
	v_div_scale_f32 v21, vcc, s10, v18, s10
	v_mul_f32_e32 v22, v21, v20
	v_fma_f32 v23, -v19, v22, v21
	v_fmac_f32_e32 v22, v23, v20
	v_fma_f32 v19, -v19, v22, v21
	v_div_fmas_f32 v19, v19, v20, v22
	v_div_fixup_f32 v19, v19, v18, s10
	v_mul_f32_e32 v14, v14, v19
	v_mov_b32_e32 v22, 0x40c00000
	v_med3_f32 v21, v14, s1, v22
	v_mul_f32_e32 v14, v15, v19
	v_med3_f32 v15, v14, s1, v22
	v_mov_b32_e32 v20, 0
	v_mul_f32_e32 v6, v6, v19
	v_mul_f32_e32 v7, v7, v19
	v_cvt_scalef32_pk_fp4_f32 v20, v21, v15, 1.0
	v_med3_f32 v6, v6, s1, v22
	v_med3_f32 v7, v7, s1, v22
	v_mov_b32_e32 v21, 0
	v_mul_f32_e32 v15, v16, v19
	v_mul_f32_e32 v16, v17, v19
	v_cvt_scalef32_pk_fp4_f32 v21, v6, v7, 1.0
	v_mul_f32_e32 v6, v8, v19
	v_mul_f32_e32 v7, v9, v19
	v_med3_f32 v15, v15, s1, v22
	v_med3_f32 v16, v16, s1, v22
	v_mul_f32_e32 v10, v10, v19
	v_mul_f32_e32 v11, v11, v19
	v_med3_f32 v6, v6, s1, v22
	v_med3_f32 v7, v7, s1, v22
	v_mul_f32_e32 v2, v2, v19
	v_mul_f32_e32 v3, v3, v19
	v_cvt_scalef32_pk_fp4_f32 v20, v15, v16, 1.0 op_sel:[0,0,1,0]
	v_med3_f32 v10, v10, s1, v22
	v_med3_f32 v11, v11, s1, v22
	v_cvt_scalef32_pk_fp4_f32 v21, v6, v7, 1.0 op_sel:[0,0,1,0]
	v_med3_f32 v2, v2, s1, v22
	v_med3_f32 v3, v3, s1, v22
	s_cselect_b64 s[8:9], -1, 0
	v_cvt_scalef32_pk_fp4_f32 v20, v10, v11, 1.0 op_sel:[0,0,0,1]
	v_mul_f32_e32 v10, v12, v19
	v_mul_f32_e32 v11, v13, v19
	v_cvt_scalef32_pk_fp4_f32 v21, v2, v3, 1.0 op_sel:[0,0,0,1]
	v_mul_f32_e32 v2, v4, v19
	v_mul_f32_e32 v3, v5, v19
	v_med3_f32 v10, v10, s1, v22
	v_med3_f32 v11, v11, s1, v22
	v_med3_f32 v2, v2, s1, v22
	v_med3_f32 v3, v3, s1, v22
	s_brev_b32 s1, 64
	s_and_b64 s[2:3], s[8:9], exec
	s_cselect_b32 s1, s1, 0x4000000
	s_add_u32 s10, s82, s1
	s_addc_u32 s11, s83, 0
	s_ashr_i32 s1, s0, 31
	s_lshl_b64 s[2:3], s[0:1], 9
	s_add_u32 s2, s10, s2
	v_mov_b32_e32 v14, 0
	v_cvt_scalef32_pk_fp4_f32 v20, v10, v11, 1.0 op_sel:[0,0,1,1]
	v_cvt_scalef32_pk_fp4_f32 v21, v2, v3, 1.0 op_sel:[0,0,1,1]
	s_addc_u32 s3, s11, s3
	global_store_dwordx2 v1, v[20:21], s[2:3]
	s_and_saveexec_b64 s[2:3], s[4:5]
	s_cbranch_execz .LBB0_925
	s_mov_b32 s10, 0x1d00000
	s_and_b64 s[4:5], s[8:9], exec
	s_cselect_b32 s4, s10, 0x1d00004
	s_add_u32 s4, s82, s4
	s_addc_u32 s5, s83, 0
	s_lshl_b64 s[0:1], s[0:1], 3
	s_add_u32 s0, s4, s0
	v_mul_f32_e32 v1, 0x3e124925, v18
	s_addc_u32 s1, s5, s1
	global_store_dword v14, v1, s[0:1]

; __device__ __forceinline__ void phase_gather_u_mfma(LAS unsigned char* lds, const bf16* X, const int* EID, float* GATE, const unsigned char* U4, const float* DQU, const float* DQV) {
;     ...
;         { const float a0 = act0 * dqu0, a1 = act1 * dqu1;
;           GATE[(size_t)t * 128 + lane] = gt0 * (0.5f * a0 * (1.f + erff(a0 * 0.70710678118654752f))) * dqv0;
;           GATE[(size_t)t * 128 + 64 + lane] = gt1 * (0.5f * a1 * (1.f + erff(a1 * 0.70710678118654752f))) * dqv1; }
;         if (!has_next) break;
;         t = tn; e0 = ne0; e1 = ne1;
.LBB0_930:
	s_or_b64 exec, exec, s[2:3]
	v_bfi_b32 v3, s33, v4, v3
	v_mul_f32_e32 v2, 0.5, v2
	v_add_f32_e32 v3, 1.0, v3
	v_mul_f32_e32 v2, v2, v3
	v_mul_f32_e32 v2, v155, v2
	v_mul_f32_e32 v2, v211, v2
	global_store_dword v[152:153], v2, off offset:256 nt
	s_and_b64 vcc, exec, s[16:17]
	v_mov_b32_e32 v154, v167
	v_mov_b32_e32 v2, v166
	s_mov_b32 s18, s14
	s_cbranch_vccnz .LBB0_957

; #define GAS __attribute__((address_space(1)))
; #define LAS __attribute__((address_space(3)))
; __device__ __forceinline__ void phase_gather_u_mfma(LAS unsigned char* lds, const bf16* X, const int* EID, float* GATE, const unsigned char* U4, const float* DQU, const float* DQV) {
;     ...
;         const int tn = t + NGW; const bool has_next = tn < T;
;         int ne0 = e0, ne1 = e1;
;         if (has_next) { ne0 = EID[(size_t)tn * 128 + lane]; ne1 = EID[(size_t)tn * 128 + 64 + lane]; }
;         const float gt0 = GATE[(size_t)t * 128 + lane], gt1 = GATE[(size_t)t * 128 + 64 + lane];
;         const float dqu0 = DQU[e0], dqu1 = DQU[e1], dqv0 = DQV[e0], dqv1 = DQV[e1];
;         { const v4u xa = *((const GAS v4u*)(X + (size_t)t * D) + 2 * lane), xb = *((const GAS v4u*)(X + (size_t)t * D) + 2 * lane + 1);
;           int w0 = 0, w1 = 0, w2 = 0, w3 = 0;
;           w0 = __builtin_amdgcn_cvt_pk_fp8_f32(bflo(xa.x), bfhi(xa.x), w0, false); w0 = __builtin_amdgcn_cvt_pk_fp8_f32(bflo(xa.y), bfhi(xa.y), w0, true);
;           w1 = __builtin_amdgcn_cvt_pk_fp8_f32(bflo(xa.z), bfhi(xa.z), w1, false); w1 = __builtin_amdgcn_cvt_pk_fp8_f32(bflo(xa.w), bfhi(xa.w), w1, true);
;           w2 = __builtin_amdgcn_cvt_pk_fp8_f32(bflo(xb.x), bfhi(xb.x), w2, false); w2 = __builtin_amdgcn_cvt_pk_fp8_f32(bflo(xb.y), bfhi(xb.y), w2, true);
;           w3 = __builtin_amdgcn_cvt_pk_fp8_f32(bflo(xb.z), bfhi(xb.z), w3, false); w3 = __builtin_amdgcn_cvt_pk_fp8_f32(bflo(xb.w), bfhi(xb.w), w3, true);
;           *(LAS v4u*)(x8 + 16 * lane) = (v4u){(unsigned)w0, (unsigned)w1, (unsigned)w2, (unsigned)w3}; }
;         float act0 = 0.f, act1 = 0.f;
;         v4u xf0[8], xf1[8];
; #pragma unroll
;         for (int ks = 0; ks < 8; ++ks) { xf0[ks] = *(const LAS v4u*)(x8 + 16 * hh + 64 * ks); xf1[ks] = *(const LAS v4u*)(x8 + 16 * hh + 64 * ks + 32); }
;         for (int q = 0; q < 4; ++q) {
; #pragma unroll
;             for (int j = 0; j < 16; ++j) *(LAS v4u*)(rows + hh * 528 + 16 * n + j * 1056) = ring[j];
;             __builtin_amdgcn_sched_barrier(0);
;             { const int qn = q + 1;
;               const int er = (qn >= 4) ? ne0 : ((qn >> 1) ? e1 : e0); const int lb = (qn >= 4) ? 0 : 32 * (qn & 1);
; #pragma unroll
;               for (int j = 0; j < 16; ++j) ULOADA(j, er, lb, j) }
.LBB0_933:
	s_ashr_i32 s19, s18, 31
	s_lshl_b64 s[2:3], s[18:19], 11
	v_lshl_add_u64 v[8:9], v[150:151], 0, s[2:3]
	global_load_dwordx4 v[4:7], v[8:9], off nt
	s_nop 0
	global_load_dwordx4 v[8:11], v[8:9], off offset:16 nt
	v_ashrrev_i32_e32 v3, 31, v2
	v_ashrrev_i32_e32 v155, 31, v154
	s_lshl_b64 s[2:3], s[18:19], 9
	v_lshlrev_b64 v[12:13], 3, v[2:3]
	v_lshlrev_b64 v[14:15], 3, v[154:155]
	v_lshl_add_u64 v[152:153], v[148:149], 0, s[2:3]
	v_lshl_add_u64 v[16:17], s[10:11], 0, v[12:13]
	v_lshl_add_u64 v[18:19], s[10:11], 0, v[14:15]
	v_lshl_add_u64 v[12:13], s[12:13], 0, v[12:13]
	v_lshl_add_u64 v[14:15], s[12:13], 0, v[14:15]
	global_load_dword v169, v[152:153], off nt
	global_load_dword v155, v[152:153], off offset:256 nt
	global_load_dwordx2 v[208:209], v[16:17], off
	global_load_dwordx2 v[210:211], v[18:19], off
	v_mov_b32_e32 v12, 0
	v_mov_b32_e32 v13, 0
	v_mov_b32_e32 v14, 0
	v_mov_b32_e32 v15, 0
	v_add_u32_e32 v173, s21, v156
	s_waitcnt vmcnt(5)
	v_lshlrev_b32_e32 v3, 16, v4
	v_and_b32_e32 v4, 0xffff0000, v4
	v_lshlrev_b32_e32 v17, 16, v6
	v_and_b32_e32 v6, 0xffff0000, v6
	s_waitcnt vmcnt(4)
	v_lshlrev_b32_e32 v19, 16, v8
	v_and_b32_e32 v8, 0xffff0000, v8
	v_lshlrev_b32_e32 v21, 16, v10
	v_and_b32_e32 v10, 0xffff0000, v10
	v_cvt_pk_fp8_f32 v12, v3, v4
	v_cvt_pk_fp8_f32 v13, v17, v6
	v_cvt_pk_fp8_f32 v14, v19, v8
	v_cvt_pk_fp8_f32 v15, v21, v10
	v_lshlrev_b32_e32 v16, 16, v5
	v_and_b32_e32 v5, 0xffff0000, v5
	v_lshlrev_b32_e32 v18, 16, v7
	v_and_b32_e32 v7, 0xffff0000, v7
	v_lshlrev_b32_e32 v20, 16, v9
	v_and_b32_e32 v9, 0xffff0000, v9
	v_lshlrev_b32_e32 v22, 16, v11
	v_and_b32_e32 v11, 0xffff0000, v11
	v_cvt_pk_fp8_f32 v12, v16, v5 op_sel:[0,0,1]
	v_cvt_pk_fp8_f32 v13, v18, v7 op_sel:[0,0,1]
	v_cvt_pk_fp8_f32 v14, v20, v9 op_sel:[0,0,1]
	v_cvt_pk_fp8_f32 v15, v22, v11 op_sel:[0,0,1]
	ds_write_b128 v158, v[12:15] offset:16896
	ds_read_b128 v[74:77], v173 offset:16896
	ds_read_b128 v[78:81], v173 offset:16928
	ds_read_b128 v[66:69], v173 offset:16960
	ds_read_b128 v[70:73], v173 offset:16992
	ds_read_b128 v[58:61], v173 offset:17024
	ds_read_b128 v[62:65], v173 offset:17056
	ds_read_b128 v[50:53], v173 offset:17088
	ds_read_b128 v[54:57], v173 offset:17120
	ds_read_b128 v[42:45], v173 offset:17152
	ds_read_b128 v[46:49], v173 offset:17184
	ds_read_b128 v[34:37], v173 offset:17216
	ds_read_b128 v[38:41], v173 offset:17248
	ds_read_b128 v[26:29], v173 offset:17280
	ds_read_b128 v[30:33], v173 offset:17312
	ds_read_b128 v[18:21], v173 offset:17344
	ds_read_b128 v[22:25], v173 offset:17376
	ds_write_b128 v161, v[82:85]
	ds_write_b128 v161, v[86:89] offset:1056
	ds_write_b128 v161, v[90:93] offset:2112
	ds_write_b128 v161, v[94:97] offset:3168
	ds_write_b128 v161, v[98:101] offset:4224
	ds_write_b128 v161, v[102:105] offset:5280
	ds_write_b128 v161, v[106:109] offset:6336
	ds_write_b128 v161, v[110:113] offset:7392
	ds_write_b128 v161, v[114:117] offset:8448
	ds_write_b128 v161, v[118:121] offset:9504
	ds_write_b128 v161, v[122:125] offset:10560
	ds_write_b128 v161, v[126:129] offset:11616
	ds_write_b128 v161, v[130:133] offset:12672
	ds_write_b128 v161, v[134:137] offset:13728
	ds_write_b128 v161, v[138:141] offset:14784
	ds_write_b128 v161, v[142:145] offset:15840
	v_readlane_b32 s2, v2, 32
	v_readlane_b32 s3, v2, 33
	s_nop 0
	v_mov_b32_e32 v4, s2
	v_mov_b32_e32 v3, s3
	v_readlane_b32 s2, v2, 34
	v_readlane_b32 s3, v2, 35
	v_cndmask_b32_e64 v3, v3, v4, s[4:5]
	v_mov_b32_e32 v5, s2
	v_mov_b32_e32 v4, s3
	v_cndmask_b32_e64 v4, v4, v5, s[4:5]
	v_lshl_or_b32 v3, v3, 9, v1
	v_lshl_or_b32 v4, v4, 9, v1
	v_readlane_b32 s2, v2, 36
	v_readlane_b32 s3, v2, 37
	global_load_dwordx4 v[82:85], v3, s[0:1]
	global_load_dwordx4 v[86:89], v4, s[0:1]
	v_mov_b32_e32 v3, s3
	v_mov_b32_e32 v4, s2
	v_readlane_b32 s2, v2, 38
	v_readlane_b32 s3, v2, 39
	v_cndmask_b32_e64 v3, v3, v4, s[4:5]
	v_mov_b32_e32 v5, s2
	v_mov_b32_e32 v4, s3
	v_cndmask_b32_e64 v4, v4, v5, s[4:5]
	v_lshl_or_b32 v3, v3, 9, v1
	v_lshl_or_b32 v4, v4, 9, v1
	v_readlane_b32 s2, v2, 40
	v_readlane_b32 s3, v2, 41
	global_load_dwordx4 v[90:93], v3, s[0:1]
	global_load_dwordx4 v[94:97], v4, s[0:1]
	v_mov_b32_e32 v3, s3
	v_mov_b32_e32 v4, s2
	v_readlane_b32 s2, v2, 42
	v_readlane_b32 s3, v2, 43
	v_cndmask_b32_e64 v3, v3, v4, s[4:5]
	v_mov_b32_e32 v5, s2
	v_mov_b32_e32 v4, s3
	v_cndmask_b32_e64 v4, v4, v5, s[4:5]
	v_lshl_or_b32 v3, v3, 9, v1
	v_lshl_or_b32 v4, v4, 9, v1
	v_readlane_b32 s2, v2, 44
	v_readlane_b32 s3, v2, 45
	global_load_dwordx4 v[98:101], v3, s[0:1]
	global_load_dwordx4 v[102:105], v4, s[0:1]
	v_mov_b32_e32 v3, s3
	v_mov_b32_e32 v4, s2
	v_readlane_b32 s2, v2, 46
	v_readlane_b32 s3, v2, 47
	v_cndmask_b32_e64 v3, v3, v4, s[4:5]
	v_mov_b32_e32 v5, s2
	v_mov_b32_e32 v4, s3
	v_cndmask_b32_e64 v4, v4, v5, s[4:5]
	v_lshl_or_b32 v3, v3, 9, v1
	v_lshl_or_b32 v4, v4, 9, v1
	v_readlane_b32 s2, v2, 48
	v_readlane_b32 s3, v2, 49
	global_load_dwordx4 v[106:109], v3, s[0:1]
	global_load_dwordx4 v[110:113], v4, s[0:1]
	v_mov_b32_e32 v3, s3
	v_mov_b32_e32 v4, s2
	v_readlane_b32 s2, v2, 50
	v_readlane_b32 s3, v2, 51
	v_cndmask_b32_e64 v3, v3, v4, s[4:5]
	v_mov_b32_e32 v5, s2
	v_mov_b32_e32 v4, s3
	v_cndmask_b32_e64 v4, v4, v5, s[4:5]
	v_lshl_or_b32 v3, v3, 9, v1
	v_lshl_or_b32 v4, v4, 9, v1
	v_readlane_b32 s2, v2, 52
	v_readlane_b32 s3, v2, 53
	global_load_dwordx4 v[114:117], v3, s[0:1]
	global_load_dwordx4 v[118:121], v4, s[0:1]
	v_mov_b32_e32 v3, s3
	v_mov_b32_e32 v4, s2
	v_readlane_b32 s2, v2, 54
	v_readlane_b32 s3, v2, 55
	v_cndmask_b32_e64 v3, v3, v4, s[4:5]
	v_mov_b32_e32 v5, s2
	v_mov_b32_e32 v4, s3
	v_cndmask_b32_e64 v4, v4, v5, s[4:5]
	v_lshl_or_b32 v3, v3, 9, v1
	v_lshl_or_b32 v4, v4, 9, v1
	v_readlane_b32 s2, v2, 56
	v_readlane_b32 s3, v2, 57
	global_load_dwordx4 v[122:125], v3, s[0:1]
	global_load_dwordx4 v[126:129], v4, s[0:1]
	v_mov_b32_e32 v3, s3
	v_mov_b32_e32 v4, s2
	v_readlane_b32 s2, v2, 58
	v_readlane_b32 s3, v2, 59
	v_cndmask_b32_e64 v3, v3, v4, s[4:5]
	v_mov_b32_e32 v5, s2
	v_mov_b32_e32 v4, s3
	v_cndmask_b32_e64 v4, v4, v5, s[4:5]
	v_lshl_or_b32 v3, v3, 9, v1
	v_lshl_or_b32 v4, v4, 9, v1
	v_readlane_b32 s2, v2, 60
	v_readlane_b32 s3, v2, 61
	global_load_dwordx4 v[130:133], v3, s[0:1]
	global_load_dwordx4 v[134:137], v4, s[0:1]
	v_mov_b32_e32 v3, s3
	v_mov_b32_e32 v4, s2
	v_readlane_b32 s2, v2, 62
	v_readlane_b32 s3, v2, 63
	v_cndmask_b32_e64 v3, v3, v4, s[4:5]
	v_mov_b32_e32 v4, s2
	v_mov_b32_e32 v2, s3
	v_lshl_or_b32 v3, v3, 9, v1
	v_cndmask_b32_e64 v2, v2, v4, s[4:5]
	v_lshl_or_b32 v2, v2, 9, v1
	global_load_dwordx4 v[138:141], v3, s[0:1]
	global_load_dwordx4 v[142:145], v2, s[0:1]
	ds_read_b128 v[2:5], v162
	ds_read_b128 v[174:177], v162 offset:32
	s_waitcnt lgkmcnt(1)
; #define LAS __attribute__((address_space(3)))
; __device__ __forceinline__ void phase_gather_u_mfma(LAS unsigned char* lds, const bf16* X, const int* EID, float* GATE, const unsigned char* U4, const float* DQU, const float* DQV) {
;     ...
;             f32x16 acc;
; #pragma unroll
;             for (int r = 0; r < 16; ++r) acc[r] = 0.f;
; #pragma unroll
;             for (int ks = 0; ks < 8; ++ks) {
;                 const v4u a4 = *(const LAS v4u*)(rows + n * 528 + 16 * hh + 32 * ks);
;                 v8i A, B;
;                 A[0] = (int)a4.x; A[1] = (int)a4.y; A[2] = (int)a4.z; A[3] = (int)a4.w; A[4] = 0; A[5] = 0; A[6] = 0; A[7] = 0;
;                 B[0] = (int)xf0[ks].x; B[1] = (int)xf0[ks].y; B[2] = (int)xf0[ks].z; B[3] = (int)xf0[ks].w; B[4] = (int)xf1[ks].x; B[5] = (int)xf1[ks].y; B[6] = (int)xf1[ks].z; B[7] = (int)xf1[ks].w;
;                 acc = __builtin_amdgcn_mfma_scale_f32_32x32x64_f8f6f4(A, B, acc, 4, 0, 0, 0x7f7f7f7f, 0, 0x7f7f7f7f);
;                 if ((ks & 1) == 1) __builtin_amdgcn_sched_barrier(0);
;             }
	v_mfma_scale_f32_32x32x64_f8f6f4 v[2:17], v[2:5], v[74:81], 0, v159, v159 op_sel_hi:[0,0,0] cbsz:4
	s_waitcnt lgkmcnt(0)
	v_mfma_scale_f32_32x32x64_f8f6f4 v[2:17], v[174:177], v[66:73], v[2:17], v159, v159 op_sel_hi:[0,0,0] cbsz:4
	ds_read_b128 v[174:177], v162 offset:64
	ds_read_b128 v[178:181], v162 offset:96
	s_waitcnt lgkmcnt(1)
	v_mfma_scale_f32_32x32x64_f8f6f4 v[2:17], v[174:177], v[58:65], v[2:17], v159, v159 op_sel_hi:[0,0,0] cbsz:4
	s_waitcnt lgkmcnt(0)
	v_mfma_scale_f32_32x32x64_f8f6f4 v[2:17], v[178:181], v[50:57], v[2:17], v159, v159 op_sel_hi:[0,0,0] cbsz:4
	ds_read_b128 v[174:177], v162 offset:128
	ds_read_b128 v[178:181], v162 offset:160
	s_waitcnt lgkmcnt(1)
	v_mfma_scale_f32_32x32x64_f8f6f4 v[2:17], v[174:177], v[42:49], v[2:17], v159, v159 op_sel_hi:[0,0,0] cbsz:4
	s_waitcnt lgkmcnt(0)
	v_mfma_scale_f32_32x32x64_f8f6f4 v[2:17], v[178:181], v[34:41], v[2:17], v159, v159 op_sel_hi:[0,0,0] cbsz:4
	ds_read_b128 v[174:177], v162 offset:192
	ds_read_b128 v[178:181], v162 offset:224
	s_waitcnt lgkmcnt(1)
	v_mfma_scale_f32_32x32x64_f8f6f4 v[2:17], v[174:177], v[26:33], v[2:17], v159, v159 op_sel_hi:[0,0,0] cbsz:4
	s_waitcnt lgkmcnt(0)
	v_mfma_scale_f32_32x32x64_f8f6f4 v[2:17], v[178:181], v[18:25], v[2:17], v159, v159 op_sel_hi:[0,0,0] cbsz:4
	v_mov_b32_e32 v174, v156
	s_mov_b32 s2, 0
	v_add_u32_e32 v174, s22, v174

; #define LAS __attribute__((address_space(3)))
; __device__ __forceinline__ void phase_gather_u_mfma(LAS unsigned char* lds, const bf16* X, const int* EID, float* GATE, const unsigned char* U4, const float* DQU, const float* DQV) {
;     ...
;             if (n == 0) {
; #pragma unroll
;                 for (int r = 0; r < 16; ++r) { const float av = acc[r]; *(LAS float*)(x8 + 1024 + 4 * ((r & 3) + 8 * (r >> 2) + 4 * hh)) = av; }
;             }
;             const float act = *(const LAS float*)(x8 + 1024 + 4 * n);
;             if (hh == (q & 1)) { if (q >> 1) act1 = act; else act0 = act; }
;         }
;         { const float a0 = act0 * dqu0, a1 = act1 * dqu1;
;           GATE[(size_t)t * 128 + lane] = gt0 * (0.5f * a0 * (1.f + erff(a0 * 0.70710678118654752f))) * dqv0;
;           GATE[(size_t)t * 128 + 64 + lane] = gt1 * (0.5f * a1 * (1.f + erff(a1 * 0.70710678118654752f))) * dqv1; }
.LBB0_949:
	s_or_b64 exec, exec, s[2:3]
	s_nop 15
	ds_read_b32 v2, v163 offset:17920
	v_cndmask_b32_e64 v3, v175, v174, s[4:5]
	v_mul_f32_e32 v3, v208, v3
	v_mul_f32_e32 v4, 0x3f3504f3, v3
	v_cmp_nlt_f32_e64 s[2:3], |v4|, 1.0
	s_and_saveexec_b64 s[18:19], s[2:3]
	s_xor_b64 s[2:3], exec, s[18:19]
	s_cbranch_execz .LBB0_951
	v_fma_f32 v5, |v4|, s23, v164
	v_fma_f32 v5, |v4|, v5, s24
	v_fma_f32 v5, |v4|, v5, s25
	v_fma_f32 v5, |v4|, v5, s26
	v_fma_f32 v5, |v4|, v5, s27
	v_fma_f32 v5, |v4|, v5, s28
	v_fma_f32 v5, |v4|, v5, |v4|
	v_mul_f32_e32 v6, 0xbfb8aa3b, v5
	v_fma_f32 v7, v5, s29, -v6
	v_rndne_f32_e32 v8, v6
	v_fmac_f32_e32 v7, 0xb2a5705f, v5
	v_sub_f32_e32 v6, v6, v8
	v_add_f32_e32 v6, v6, v7
	v_cvt_i32_f32_e32 v7, v8
	v_exp_f32_e32 v6, v6
	v_cmp_nlt_f32_e32 vcc, s30, v5
	v_ldexp_f32 v6, v6, v7
	s_nop 0
	v_cndmask_b32_e32 v6, 0, v6, vcc
	v_cmp_ngt_f32_e32 vcc, s31, v5
	s_nop 1
	v_cndmask_b32_e32 v5, v165, v6, vcc
	v_sub_f32_e32 v5, 1.0, v5
.LBB0_951:
	s_andn2_saveexec_b64 s[2:3], s[2:3]
	v_mul_f32_e32 v5, v4, v4
	v_fmamk_f32 v6, v5, 0xba1345e1, v160
	v_fmaak_f32 v6, v5, v6, 0xbcdac9b8
	v_fmaak_f32 v6, v5, v6, 0x3de703be
	v_fmaak_f32 v6, v5, v6, 0xbec09330
	v_fmaak_f32 v5, v5, v6, 0x3e0375d0
	v_fma_f32 v5, |v4|, v5, |v4|
	s_or_b64 exec, exec, s[2:3]
	v_bfi_b32 v4, s33, v5, v4
	v_mul_f32_e32 v3, 0.5, v3
	v_add_f32_e32 v4, 1.0, v4
	v_mul_f32_e32 v3, v3, v4
	s_waitcnt lgkmcnt(0)
	v_cndmask_b32_e64 v2, v2, v154, s[4:5]
	v_mul_f32_e32 v3, v169, v3
	v_mul_f32_e32 v2, v210, v2
	v_mul_f32_e32 v3, v209, v3
	global_store_dword v[152:153], v3, off nt
	v_mul_f32_e32 v3, 0x3f3504f3, v2
	v_cmp_nlt_f32_e64 s[2:3], |v3|, 1.0
	s_and_saveexec_b64 s[18:19], s[2:3]
	s_xor_b64 s[2:3], exec, s[18:19]
	s_cbranch_execz .LBB0_955
	v_fma_f32 v4, |v3|, s23, v164
	v_fma_f32 v4, |v3|, v4, s24
	v_fma_f32 v4, |v3|, v4, s25
	v_fma_f32 v4, |v3|, v4, s26
	v_fma_f32 v4, |v3|, v4, s27
	v_fma_f32 v4, |v3|, v4, s28
	v_fma_f32 v4, |v3|, v4, |v3|
	v_mul_f32_e32 v5, 0xbfb8aa3b, v4
	v_fma_f32 v6, v4, s29, -v5
	v_rndne_f32_e32 v7, v5
	v_fmac_f32_e32 v6, 0xb2a5705f, v4
	v_sub_f32_e32 v5, v5, v7
	v_add_f32_e32 v5, v5, v6
	v_cvt_i32_f32_e32 v6, v7
	v_exp_f32_e32 v5, v5
	v_cmp_nlt_f32_e32 vcc, s30, v4
	v_ldexp_f32 v5, v5, v6
	s_nop 0
	v_cndmask_b32_e32 v5, 0, v5, vcc
	v_cmp_ngt_f32_e32 vcc, s31, v4
	s_nop 1
	v_cndmask_b32_e32 v4, v165, v5, vcc
	v_sub_f32_e32 v4, 1.0, v4

; #define GAS __attribute__((address_space(1)))
; #define Q4(x) fminf(fmaxf((x) * sc, -6.f), 6.f)
; #define Q4(x) fminf(fmaxf((x) * sc, -6.f), 6.f)
; __device__ __forceinline__ void table_row_to_fp4(const f32x4 (&v)[4], int lane, bool isv, int r, unsigned char* ws) {
;     float m = 0.f;
; #pragma unroll
;     for (int j = 0; j < 4; ++j) m = fmaxf(fmaxf(m, fmaxf(fabsf(v[j].x), fabsf(v[j].y))), fmaxf(fabsf(v[j].z), fabsf(v[j].w)));
; #pragma unroll
;     for (int o = 1; o < 64; o <<= 1) m = fmaxf(m, __shfl_xor(m, o));
;     m = fmaxf(m, 1e-30f);
;     const float sc = 7.f / m;
;     unsigned w0 = 0u, w1 = 0u;
;     ...
;     w0 = __builtin_amdgcn_cvt_scalef32_pk_fp4_f32(w0, Q4(v[0].x), Q4(v[0].y), 1.0f, 0); w0 = __builtin_amdgcn_cvt_scalef32_pk_fp4_f32(w0, Q4(v[0].z), Q4(v[0].w), 1.0f, 1);
;     w0 = __builtin_amdgcn_cvt_scalef32_pk_fp4_f32(w0, Q4(v[1].x), Q4(v[1].y), 1.0f, 2); w0 = __builtin_amdgcn_cvt_scalef32_pk_fp4_f32(w0, Q4(v[1].z), Q4(v[1].w), 1.0f, 3);
;     w1 = __builtin_amdgcn_cvt_scalef32_pk_fp4_f32(w1, Q4(v[2].x), Q4(v[2].y), 1.0f, 0); w1 = __builtin_amdgcn_cvt_scalef32_pk_fp4_f32(w1, Q4(v[2].z), Q4(v[2].w), 1.0f, 1);
;     w1 = __builtin_amdgcn_cvt_scalef32_pk_fp4_f32(w1, Q4(v[3].x), Q4(v[3].y), 1.0f, 2); w1 = __builtin_amdgcn_cvt_scalef32_pk_fp4_f32(w1, Q4(v[3].z), Q4(v[3].w), 1.0f, 3);
;     ...
;     *((GAS v2u*)(ws + (isv ? WS_V8 : WS_U8) + (size_t)r * 512) + lane) = (v2u){w0, w1};
;     if (lane == 0) ((float*)(ws + (isv ? WS_DQV : WS_DQU)))[r] = m * (1.f / 7.f);
; __device__ __forceinline__ void barrier_side_convert(int k, const float* U, const float* V, unsigned char* ws) {
;     ...
;         if (j < RB && g0 + j < glim) { const int g = g0 + j, tb = g >> 14, r = NEXP * (tb >> 1) + (g & (NEXP - 1)); const GAS f32x4* src = (const GAS f32x4*)(((tb & 1) ? V : U) + (size_t)r * D) + 4 * lane;
; #pragma unroll
;             for (int q = 0; q < 4; ++q) v[jj][q] = src[q]; } }
; #pragma unroll
;     for (int jj = 0; jj < 3; ++jj) { const int j = wave - 1 + 7 * jj;
;         if (j < RB && g0 + j < glim) { const int g = g0 + j, tb = g >> 14, r = NEXP * (tb >> 1) + (g & (NEXP - 1)); table_row_to_fp4(v[jj], lane, (tb & 1) != 0, r, ws); } }
.LBB0_1031:
	s_andn2_b64 vcc, exec, s[6:7]
	s_cbranch_vccnz .LBB0_1036
	s_add_i32 s15, s15, s14
	s_cmp_gt_i32 s15, 0xffff
	s_cbranch_scc1 .LBB0_1036
	s_waitcnt vmcnt(0)
	v_max_f32_e64 v18, |v15|, |v15|
	v_max_f32_e64 v19, |v14|, |v14|
	v_max_f32_e32 v18, v19, v18
	v_max_f32_e64 v19, |v17|, |v17|
	v_max_f32_e64 v20, |v16|, |v16|
	v_max_f32_e32 v19, v20, v19
	v_max3_f32 v18, v18, 0, v19
	v_max_f32_e64 v19, |v11|, |v11|
	v_max_f32_e64 v20, |v10|, |v10|
	v_max_f32_e32 v19, v20, v19
	v_max_f32_e64 v20, |v13|, |v13|
	v_max_f32_e64 v21, |v12|, |v12|
	v_max_f32_e32 v20, v21, v20
	v_max3_f32 v18, v18, v19, v20
	v_max_f32_e64 v19, |v7|, |v7|
	v_max_f32_e64 v20, |v6|, |v6|
	v_max_f32_e32 v19, v20, v19
	v_max_f32_e64 v20, |v9|, |v9|
	v_max_f32_e64 v21, |v8|, |v8|
	v_max_f32_e32 v20, v21, v20
	v_max3_f32 v18, v18, v19, v20
	v_max_f32_e64 v19, |v3|, |v3|
	v_max_f32_e64 v20, |v2|, |v2|
	v_max_f32_e32 v19, v20, v19
	v_max_f32_e64 v20, |v5|, |v5|
	v_max_f32_e64 v21, |v4|, |v4|
	v_max_f32_e32 v20, v21, v20
	v_max3_f32 v18, v18, v19, v20
	v_mbcnt_lo_u32_b32 v19, -1, 0
	v_mbcnt_hi_u32_b32 v19, -1, v19
	v_and_b32_e32 v20, 64, v19
	v_add_u32_e32 v20, 64, v20
	v_xor_b32_e32 v21, 1, v19
	v_cmp_lt_i32_e32 vcc, v21, v20
	s_ashr_i32 s2, s15, 1
	s_and_b32 s6, s2, 0xffffc000
	v_cndmask_b32_e32 v21, v19, v21, vcc
	v_lshlrev_b32_e32 v21, 2, v21
	ds_bpermute_b32 v21, v21, v18
	s_mov_b32 s2, 0xda24260
	s_mov_b32 s10, 0x40e00000
	s_and_b32 s7, s15, 0x3fff
	s_or_b32 s6, s6, s7
	s_waitcnt lgkmcnt(0)
	v_max_f32_e32 v21, v21, v21
	v_max_f32_e32 v18, v18, v21
	v_xor_b32_e32 v21, 2, v19
	v_cmp_lt_i32_e32 vcc, v21, v20
	s_bitcmp0_b32 s15, 14
	s_cselect_b64 s[8:9], -1, 0
	v_cndmask_b32_e32 v21, v19, v21, vcc
	v_lshlrev_b32_e32 v21, 2, v21
	ds_bpermute_b32 v21, v21, v18
	s_brev_b32 s7, 64
	v_lshlrev_b32_e32 v1, 3, v1
	s_waitcnt lgkmcnt(0)
	v_max_f32_e32 v21, v21, v21
	v_max_f32_e32 v18, v18, v21
	v_xor_b32_e32 v21, 4, v19
	v_cmp_lt_i32_e32 vcc, v21, v20
	s_nop 1
	v_cndmask_b32_e32 v21, v19, v21, vcc
	v_lshlrev_b32_e32 v21, 2, v21
	ds_bpermute_b32 v21, v21, v18
	s_waitcnt lgkmcnt(0)
	v_max_f32_e32 v21, v21, v21
	v_max_f32_e32 v18, v18, v21
	v_xor_b32_e32 v21, 8, v19
	v_cmp_lt_i32_e32 vcc, v21, v20
	s_nop 1
	v_cndmask_b32_e32 v21, v19, v21, vcc
	v_lshlrev_b32_e32 v21, 2, v21
	ds_bpermute_b32 v21, v21, v18
	s_waitcnt lgkmcnt(0)
	v_max_f32_e32 v21, v21, v21
	v_max_f32_e32 v18, v18, v21
	v_xor_b32_e32 v21, 16, v19
	v_cmp_lt_i32_e32 vcc, v21, v20
	s_nop 1
	v_cndmask_b32_e32 v21, v19, v21, vcc
	v_lshlrev_b32_e32 v21, 2, v21
	ds_bpermute_b32 v21, v21, v18
	s_waitcnt lgkmcnt(0)
	v_max_f32_e32 v21, v21, v21
	v_max_f32_e32 v18, v18, v21
	v_xor_b32_e32 v21, 32, v19
	v_cmp_lt_i32_e32 vcc, v21, v20
	s_nop 1
	v_cndmask_b32_e32 v19, v19, v21, vcc
	v_lshlrev_b32_e32 v19, 2, v19
	ds_bpermute_b32 v19, v19, v18
	s_waitcnt lgkmcnt(0)
	v_max3_f32 v18, v18, v19, s2
	v_div_scale_f32 v19, s[2:3], v18, v18, s10
	v_rcp_f32_e32 v20, v19
	s_mov_b32 s2, 0xc0c00000
	v_fma_f32 v21, -v19, v20, 1.0
	v_fmac_f32_e32 v20, v21, v20
	v_div_scale_f32 v21, vcc, s10, v18, s10
	v_mul_f32_e32 v22, v21, v20
	v_fma_f32 v23, -v19, v22, v21
	v_fmac_f32_e32 v22, v23, v20
	v_fma_f32 v19, -v19, v22, v21
	v_div_fmas_f32 v19, v19, v20, v22
	v_div_fixup_f32 v19, v19, v18, s10
	v_mul_f32_e32 v14, v14, v19
	v_mov_b32_e32 v22, 0x40c00000
	v_med3_f32 v21, v14, s2, v22
	v_mul_f32_e32 v14, v15, v19
	v_med3_f32 v15, v14, s2, v22
	v_mov_b32_e32 v20, 0
	v_mul_f32_e32 v6, v6, v19
	v_mul_f32_e32 v7, v7, v19
	v_cvt_scalef32_pk_fp4_f32 v20, v21, v15, 1.0
	v_med3_f32 v6, v6, s2, v22
	v_med3_f32 v7, v7, s2, v22
	v_mov_b32_e32 v21, 0
	v_mul_f32_e32 v15, v16, v19
	v_mul_f32_e32 v16, v17, v19
	v_cvt_scalef32_pk_fp4_f32 v21, v6, v7, 1.0
	v_mul_f32_e32 v6, v8, v19
	v_mul_f32_e32 v7, v9, v19
	v_med3_f32 v15, v15, s2, v22
	v_med3_f32 v16, v16, s2, v22
	v_mul_f32_e32 v10, v10, v19
	v_mul_f32_e32 v11, v11, v19
	v_med3_f32 v6, v6, s2, v22
	v_med3_f32 v7, v7, s2, v22
	v_mul_f32_e32 v2, v2, v19
	v_mul_f32_e32 v3, v3, v19
	v_cvt_scalef32_pk_fp4_f32 v20, v15, v16, 1.0 op_sel:[0,0,1,0]
	v_med3_f32 v10, v10, s2, v22
	v_med3_f32 v11, v11, s2, v22
	v_cvt_scalef32_pk_fp4_f32 v21, v6, v7, 1.0 op_sel:[0,0,1,0]
	v_med3_f32 v2, v2, s2, v22
	v_med3_f32 v3, v3, s2, v22
	v_cvt_scalef32_pk_fp4_f32 v20, v10, v11, 1.0 op_sel:[0,0,0,1]
	v_mul_f32_e32 v10, v12, v19
	v_mul_f32_e32 v11, v13, v19
	v_cvt_scalef32_pk_fp4_f32 v21, v2, v3, 1.0 op_sel:[0,0,0,1]
	v_mul_f32_e32 v2, v4, v19
	v_mul_f32_e32 v3, v5, v19
	v_med3_f32 v10, v10, s2, v22
	v_med3_f32 v11, v11, s2, v22
	v_med3_f32 v2, v2, s2, v22
	v_med3_f32 v3, v3, s2, v22
	s_and_b64 s[2:3], s[8:9], exec
	s_cselect_b32 s2, s7, 0x4000000
	s_add_u32 s10, s82, s2
	s_addc_u32 s11, s83, 0
	s_ashr_i32 s7, s6, 31
	s_lshl_b64 s[2:3], s[6:7], 9
	s_add_u32 s2, s10, s2
	v_mov_b32_e32 v14, 0
	v_cvt_scalef32_pk_fp4_f32 v20, v10, v11, 1.0 op_sel:[0,0,1,1]
	v_cvt_scalef32_pk_fp4_f32 v21, v2, v3, 1.0 op_sel:[0,0,1,1]
	s_addc_u32 s3, s11, s3
	global_store_dwordx2 v1, v[20:21], s[2:3]
	s_and_saveexec_b64 s[2:3], s[4:5]
	s_cbranch_execz .LBB0_1035
	s_mov_b32 s10, 0x1d00000
	s_and_b64 s[4:5], s[8:9], exec
	s_cselect_b32 s4, s10, 0x1d00004
	s_add_u32 s8, s82, s4
	s_addc_u32 s9, s83, 0
	s_lshl_b64 s[4:5], s[6:7], 3
	s_add_u32 s4, s8, s4
	v_mul_f32_e32 v1, 0x3e124925, v18
	s_addc_u32 s5, s9, s5
	global_store_dword v14, v1, s[4:5]

; #define LAS __attribute__((address_space(3)))
; #define ULOADA(slot, ereg, lb, j_) { const int ea_ = __builtin_amdgcn_readlane((ereg), (lb) + 2 * (j_)), eb_ = __builtin_amdgcn_readlane((ereg), (lb) + 2 * (j_) + 1); const int el_ = hh ? eb_ : ea_; \
;         ring[slot] = *(const GAS v4u*)(U4 + (((unsigned)el_ << 9) + laneoff)); }
; __device__ __forceinline__ void phase_gather_u_mfma(LAS unsigned char* lds, const bf16* X, const int* EID, float* GATE, const unsigned char* U4, const float* DQU, const float* DQV) {
;     const int tid = threadIdx.x, lane = tid & 63, wave = __builtin_amdgcn_readfirstlane(tid >> 6);
;     const int gw = blockIdx.x * NWAVES + wave, NGW = gridDim.x * NWAVES;
;     const int n = lane & 31, hh = lane >> 5;
;     LAS unsigned char* rows = lds + wave * 18048;
;     LAS unsigned char* x8 = rows + 16896;
;     const unsigned laneoff = 16u * (unsigned)n;
;     int t = gw;
;     if (t < T) {
;     int e0 = EID[(size_t)t * 128 + lane], e1 = EID[(size_t)t * 128 + 64 + lane];
;     v4u ring[16];
;     ...
; #pragma unroll
;     for (int j = 0; j < 16; ++j) ULOADA(j, e0, 0, j)
.LBB0_1893:
	s_cmp_lt_i32 s68, 17
	s_cselect_b64 s[8:9], -1, 0
	s_and_b64 s[0:1], s[8:9], s[6:7]
	s_andn2_b64 vcc, exec, s[0:1]
	s_cbranch_vccnz .LBB0_1923
	v_readfirstlane_b32 s1, v0
	s_lshl_b32 s0, s88, 3
	s_lshr_b32 s2, s1, 6
	s_add_i32 s18, s2, s0
	s_cmpk_gt_i32 s18, 0x7fff
	s_cbranch_scc1 .LBB0_1923
	s_add_u32 s0, s82, 0x2800000
	s_addc_u32 s1, s83, 0
	s_add_u32 s10, s82, 0x1d20000
	s_addc_u32 s11, s83, 0
	s_add_u32 s12, s82, 0x1d30000
	s_waitcnt vmcnt(0)
	v_and_b32_e32 v3, 63, v0
	s_addc_u32 s13, s83, 0
	v_lshlrev_b32_e32 v4, 2, v3
	v_mov_b32_e32 v5, 0
	s_ashr_i32 s19, s18, 31
	v_lshl_add_u64 v[146:147], s[60:61], 0, v[4:5]
	s_lshl_b64 s[4:5], s[18:19], 9
	v_lshl_add_u64 v[6:7], v[146:147], 0, s[4:5]
	global_load_dword v2, v[6:7], off nt
	global_load_dword v154, v[6:7], off offset:256 nt
	v_and_b32_e32 v8, 31, v0
	v_lshlrev_b32_e32 v1, 4, v8
	s_mulk_i32 s2, 0x4680
	v_lshl_add_u64 v[148:149], s[70:71], 0, v[4:5]
	v_lshlrev_b32_e32 v156, 4, v186
	v_mov_b32_e32 v159, 0x7f7f7f7f
	v_mov_b32_e32 v160, 0x3ba10414
	s_brev_b32 s33, -2
	v_mov_b32_e32 v164, 0xb9c68948
	v_mov_b32_e32 v165, 0x7f800000
	s_waitcnt vmcnt(1)
	v_readlane_b32 s3, v2, 0
	v_readlane_b32 s4, v2, 1
	v_readlane_b32 s5, v2, 2
	v_readlane_b32 s6, v2, 3
	v_readlane_b32 s7, v2, 4
	v_readlane_b32 s14, v2, 5
	v_readlane_b32 s15, v2, 6
	v_readlane_b32 s16, v2, 7
	v_readlane_b32 s17, v2, 8
	v_readlane_b32 s19, v2, 9
	v_readlane_b32 s20, v2, 10
	v_readlane_b32 s21, v2, 11
	v_readlane_b32 s22, v2, 12
	v_readlane_b32 s23, v2, 13
	v_readlane_b32 s24, v2, 14
	v_readlane_b32 s25, v2, 15
	v_readlane_b32 s26, v2, 16
	v_readlane_b32 s27, v2, 17
	v_readlane_b32 s28, v2, 18
	v_readlane_b32 s29, v2, 19
	v_mov_b32_e32 v6, s4
	v_mov_b32_e32 v7, s3
	v_mov_b32_e32 v9, s6
	v_mov_b32_e32 v10, s5
	v_mov_b32_e32 v11, s14
	v_mov_b32_e32 v12, s7
	v_cmp_gt_u32_e64 s[4:5], 32, v3
	v_mov_b32_e32 v13, s16
	v_mov_b32_e32 v14, s15
	v_mov_b32_e32 v15, s19
	v_mov_b32_e32 v16, s17
	v_mov_b32_e32 v17, s21
	v_mov_b32_e32 v18, s20
	v_mov_b32_e32 v19, s23
	v_mov_b32_e32 v20, s22
	v_mov_b32_e32 v21, s25
	v_mov_b32_e32 v22, s24
	v_mov_b32_e32 v23, s27
	v_mov_b32_e32 v24, s26
	v_mov_b32_e32 v25, s29
	v_mov_b32_e32 v26, s28
	v_cndmask_b32_e64 v6, v6, v7, s[4:5]
	v_cndmask_b32_e64 v7, v9, v10, s[4:5]
	v_cndmask_b32_e64 v9, v11, v12, s[4:5]
	v_readlane_b32 s30, v2, 20
	v_readlane_b32 s31, v2, 21
	v_cndmask_b32_e64 v10, v13, v14, s[4:5]
	v_cndmask_b32_e64 v11, v15, v16, s[4:5]
	v_cndmask_b32_e64 v12, v17, v18, s[4:5]
	v_cndmask_b32_e64 v13, v19, v20, s[4:5]
	v_cndmask_b32_e64 v14, v21, v22, s[4:5]
	v_cndmask_b32_e64 v15, v23, v24, s[4:5]
	v_cndmask_b32_e64 v16, v25, v26, s[4:5]
	v_lshl_or_b32 v6, v6, 9, v1
	v_lshl_or_b32 v7, v7, 9, v1
	v_lshl_or_b32 v9, v9, 9, v1
	v_readlane_b32 s3, v2, 22
	v_readlane_b32 s6, v2, 23
	v_mov_b32_e32 v27, s31
	v_mov_b32_e32 v28, s30
	v_lshl_or_b32 v10, v10, 9, v1
	v_lshl_or_b32 v11, v11, 9, v1
	v_lshl_or_b32 v12, v12, 9, v1
	v_lshl_or_b32 v13, v13, 9, v1
	v_lshl_or_b32 v14, v14, 9, v1
	v_lshl_or_b32 v15, v15, 9, v1
	v_lshl_or_b32 v16, v16, 9, v1
	global_load_dwordx4 v[82:85], v6, s[0:1]
	global_load_dwordx4 v[86:89], v7, s[0:1]
	global_load_dwordx4 v[90:93], v9, s[0:1]
	global_load_dwordx4 v[94:97], v10, s[0:1]
	global_load_dwordx4 v[98:101], v11, s[0:1]
	global_load_dwordx4 v[102:105], v12, s[0:1]
	global_load_dwordx4 v[106:109], v13, s[0:1]
	global_load_dwordx4 v[110:113], v14, s[0:1]
	global_load_dwordx4 v[114:117], v15, s[0:1]
	global_load_dwordx4 v[118:121], v16, s[0:1]
	v_mov_b32_e32 v7, s6
	v_mov_b32_e32 v9, s3
	v_cndmask_b32_e64 v17, v27, v28, s[4:5]
	v_cndmask_b32_e64 v7, v7, v9, s[4:5]
	v_lshl_or_b32 v6, v17, 9, v1
	v_lshl_or_b32 v7, v7, 9, v1
	v_readlane_b32 s3, v2, 24
	v_readlane_b32 s6, v2, 25
	global_load_dwordx4 v[122:125], v6, s[0:1]
	global_load_dwordx4 v[126:129], v7, s[0:1]
	v_mov_b32_e32 v6, s6
	v_mov_b32_e32 v7, s3
	v_readlane_b32 s3, v2, 26
	v_readlane_b32 s6, v2, 27
	v_cndmask_b32_e64 v6, v6, v7, s[4:5]
	v_mov_b32_e32 v9, s3
	v_mov_b32_e32 v7, s6
	v_cndmask_b32_e64 v7, v7, v9, s[4:5]
	v_lshl_or_b32 v6, v6, 9, v1
	v_lshl_or_b32 v7, v7, 9, v1
	v_readlane_b32 s3, v2, 28
	v_readlane_b32 s6, v2, 29
	global_load_dwordx4 v[130:133], v6, s[0:1]
	global_load_dwordx4 v[134:137], v7, s[0:1]
	v_mov_b32_e32 v6, s6
	v_mov_b32_e32 v7, s3
	v_readlane_b32 s3, v2, 30
	v_readlane_b32 s6, v2, 31
	v_cndmask_b32_e64 v6, v6, v7, s[4:5]
	v_mov_b32_e32 v9, s3
	v_mov_b32_e32 v7, s6
	v_lshl_or_b32 v6, v6, 9, v1
	v_cndmask_b32_e64 v7, v7, v9, s[4:5]
	v_lshl_or_b32 v7, v7, 9, v1
	global_load_dwordx4 v[138:141], v6, s[0:1]
	global_load_dwordx4 v[142:145], v7, s[0:1]
	s_add_i32 s21, s2, 0
	s_movk_i32 s3, 0x210
	v_mov_b32_e32 v4, s21
	v_lshlrev_b32_e32 v7, 4, v3
	v_mad_u32_u24 v9, v186, s3, v4
	v_mad_u32_u24 v10, v8, s3, v4
	v_lshlrev_b32_e32 v4, 5, v3
	v_mov_b32_e32 v3, s2
	v_readlane_b32 s6, v255, 9
	v_mad_u32_u24 v3, v8, s3, v3
	v_readlane_b32 s7, v255, 10
	v_lshlrev_b32_e32 v6, 2, v8
	v_add3_u32 v3, v3, v156, 0
	s_lshl_b32 s20, s6, 3
	v_cmp_eq_u32_e64 s[6:7], 0, v8
	v_lshl_add_u64 v[150:151], s[62:63], 0, v[4:5]
	v_add_u32_e32 v157, 0x100, v3
	s_add_i32 s22, s21, 0x4400
	v_add_u32_e32 v158, s21, v7
	s_mov_b32 s23, 0x378e98ab
	s_mov_b32 s24, 0x3b7cd369
	s_mov_b32 s25, 0xbcc618b2
	s_mov_b32 s26, 0x3dda74e4
	s_mov_b32 s27, 0x3f228afd
	s_mov_b32 s28, 0x3e03c728
	s_mov_b32 s29, 0xbfb8aa3b
	s_mov_b32 s30, 0x42ce8ed0
	s_mov_b32 s31, 0xc2b17218
	v_add_u32_e32 v161, v9, v1
	v_add_u32_e32 v162, v10, v156
	v_add_u32_e32 v163, s21, v6
	s_branch .LBB0_1897

; #define GAS __attribute__((address_space(1)))
; #define Q4(x) fminf(fmaxf((x) * sc, -6.f), 6.f)
; #define Q4(x) fminf(fmaxf((x) * sc, -6.f), 6.f)
; __device__ __forceinline__ void table_row_to_fp4(const f32x4 (&v)[4], int lane, bool isv, int r, unsigned char* ws) {
;     float m = 0.f;
; #pragma unroll
;     for (int j = 0; j < 4; ++j) m = fmaxf(fmaxf(m, fmaxf(fabsf(v[j].x), fabsf(v[j].y))), fmaxf(fabsf(v[j].z), fabsf(v[j].w)));
; #pragma unroll
;     for (int o = 1; o < 64; o <<= 1) m = fmaxf(m, __shfl_xor(m, o));
;     m = fmaxf(m, 1e-30f);
;     const float sc = 7.f / m;
;     unsigned w0 = 0u, w1 = 0u;
;     ...
;     w0 = __builtin_amdgcn_cvt_scalef32_pk_fp4_f32(w0, Q4(v[0].x), Q4(v[0].y), 1.0f, 0); w0 = __builtin_amdgcn_cvt_scalef32_pk_fp4_f32(w0, Q4(v[0].z), Q4(v[0].w), 1.0f, 1);
;     w0 = __builtin_amdgcn_cvt_scalef32_pk_fp4_f32(w0, Q4(v[1].x), Q4(v[1].y), 1.0f, 2); w0 = __builtin_amdgcn_cvt_scalef32_pk_fp4_f32(w0, Q4(v[1].z), Q4(v[1].w), 1.0f, 3);
;     w1 = __builtin_amdgcn_cvt_scalef32_pk_fp4_f32(w1, Q4(v[2].x), Q4(v[2].y), 1.0f, 0); w1 = __builtin_amdgcn_cvt_scalef32_pk_fp4_f32(w1, Q4(v[2].z), Q4(v[2].w), 1.0f, 1);
;     w1 = __builtin_amdgcn_cvt_scalef32_pk_fp4_f32(w1, Q4(v[3].x), Q4(v[3].y), 1.0f, 2); w1 = __builtin_amdgcn_cvt_scalef32_pk_fp4_f32(w1, Q4(v[3].z), Q4(v[3].w), 1.0f, 3);
;     ...
;     *((GAS v2u*)(ws + (isv ? WS_V8 : WS_U8) + (size_t)r * 512) + lane) = (v2u){w0, w1};
;     if (lane == 0) ((float*)(ws + (isv ? WS_DQV : WS_DQU)))[r] = m * (1.f / 7.f);
; __device__ __forceinline__ void barrier_side_convert(int k, const float* U, const float* V, unsigned char* ws) {
;     ...
;         if (j < RB && g0 + j < glim) { const int g = g0 + j, tb = g >> 14, r = NEXP * (tb >> 1) + (g & (NEXP - 1)); const GAS f32x4* src = (const GAS f32x4*)(((tb & 1) ? V : U) + (size_t)r * D) + 4 * lane;
; #pragma unroll
;             for (int q = 0; q < 4; ++q) v[jj][q] = src[q]; } }
; #pragma unroll
;     for (int jj = 0; jj < 3; ++jj) { const int j = wave - 1 + 7 * jj;
;         if (j < RB && g0 + j < glim) { const int g = g0 + j, tb = g >> 14, r = NEXP * (tb >> 1) + (g & (NEXP - 1)); table_row_to_fp4(v[jj], lane, (tb & 1) != 0, r, ws); } }
.LBB0_2073:
	s_andn2_b64 vcc, exec, s[0:1]
	v_cmp_eq_u32_e64 s[0:1], 0, v48
	s_cbranch_vccnz .LBB0_2078
	s_add_i32 s7, s6, s12
	s_cmp_gt_i32 s7, 0xffff
	s_cbranch_scc1 .LBB0_2078
	s_waitcnt vmcnt(0)
	v_max_f32_e64 v49, |v45|, |v45|
	v_max_f32_e64 v50, |v44|, |v44|
	v_max_f32_e32 v49, v50, v49
	v_max_f32_e64 v50, |v47|, |v47|
	v_max_f32_e64 v51, |v46|, |v46|
	v_max_f32_e32 v50, v51, v50
	v_max3_f32 v49, v49, 0, v50
	v_max_f32_e64 v50, |v41|, |v41|
	v_max_f32_e64 v51, |v40|, |v40|
	v_max_f32_e32 v50, v51, v50
	v_max_f32_e64 v51, |v43|, |v43|
	v_max_f32_e64 v52, |v42|, |v42|
	v_max_f32_e32 v51, v52, v51
	v_max3_f32 v49, v49, v50, v51
	v_max_f32_e64 v50, |v37|, |v37|
	v_max_f32_e64 v51, |v36|, |v36|
	v_max_f32_e32 v50, v51, v50
	v_max_f32_e64 v51, |v39|, |v39|
	v_max_f32_e64 v52, |v38|, |v38|
	v_max_f32_e32 v51, v52, v51
	v_max3_f32 v49, v49, v50, v51
	v_max_f32_e64 v50, |v33|, |v33|
	v_max_f32_e64 v51, |v32|, |v32|
	v_max_f32_e32 v50, v51, v50
	v_max_f32_e64 v51, |v35|, |v35|
	v_max_f32_e64 v52, |v34|, |v34|
	v_max_f32_e32 v51, v52, v51
	v_max3_f32 v49, v49, v50, v51
	v_mbcnt_lo_u32_b32 v50, -1, 0
	v_mbcnt_hi_u32_b32 v50, -1, v50
	v_and_b32_e32 v51, 64, v50
	v_add_u32_e32 v51, 64, v51
	v_xor_b32_e32 v52, 1, v50
	v_cmp_lt_i32_e32 vcc, v52, v51
	s_mov_b32 s8, 0xda24260
	s_mov_b32 s11, 0x40e00000
	v_cndmask_b32_e32 v52, v50, v52, vcc
	v_lshlrev_b32_e32 v52, 2, v52
	ds_bpermute_b32 v52, v52, v49
	s_ashr_i32 s6, s7, 1
	s_and_b32 s6, s6, 0xffffc000
	s_and_b32 s10, s7, 0x3fff
	s_or_b32 s6, s6, s10
	s_waitcnt lgkmcnt(0)
	v_max_f32_e32 v52, v52, v52
	v_max_f32_e32 v49, v49, v52
	v_xor_b32_e32 v52, 2, v50
	v_cmp_lt_i32_e32 vcc, v52, v51
	s_bitcmp0_b32 s7, 14
	s_mov_b32 s7, 0xc0c00000
	v_cndmask_b32_e32 v52, v50, v52, vcc
	v_lshlrev_b32_e32 v52, 2, v52
	ds_bpermute_b32 v52, v52, v49
	s_waitcnt lgkmcnt(0)
	v_max_f32_e32 v52, v52, v52
	v_max_f32_e32 v49, v49, v52
	v_xor_b32_e32 v52, 4, v50
	v_cmp_lt_i32_e32 vcc, v52, v51
	s_nop 1
	v_cndmask_b32_e32 v52, v50, v52, vcc
	v_lshlrev_b32_e32 v52, 2, v52
	ds_bpermute_b32 v52, v52, v49
	s_waitcnt lgkmcnt(0)
	v_max_f32_e32 v52, v52, v52
	v_max_f32_e32 v49, v49, v52
	v_xor_b32_e32 v52, 8, v50
	v_cmp_lt_i32_e32 vcc, v52, v51
	s_nop 1
	v_cndmask_b32_e32 v52, v50, v52, vcc
	v_lshlrev_b32_e32 v52, 2, v52
	ds_bpermute_b32 v52, v52, v49
	s_waitcnt lgkmcnt(0)
	v_max_f32_e32 v52, v52, v52
	v_max_f32_e32 v49, v49, v52
	v_xor_b32_e32 v52, 16, v50
	v_cmp_lt_i32_e32 vcc, v52, v51
	s_nop 1
	v_cndmask_b32_e32 v52, v50, v52, vcc
	v_lshlrev_b32_e32 v52, 2, v52
	ds_bpermute_b32 v52, v52, v49
	s_waitcnt lgkmcnt(0)
	v_max_f32_e32 v52, v52, v52
	v_max_f32_e32 v49, v49, v52
	v_xor_b32_e32 v52, 32, v50
	v_cmp_lt_i32_e32 vcc, v52, v51
	s_nop 1
	v_cndmask_b32_e32 v50, v50, v52, vcc
	v_lshlrev_b32_e32 v50, 2, v50
	ds_bpermute_b32 v50, v50, v49
	s_waitcnt lgkmcnt(0)
	v_max3_f32 v49, v49, v50, s8
	v_div_scale_f32 v50, s[8:9], v49, v49, s11
	v_rcp_f32_e32 v51, v50
	s_cselect_b64 s[8:9], -1, 0
	v_fma_f32 v52, -v50, v51, 1.0
	v_fmac_f32_e32 v51, v52, v51
	v_div_scale_f32 v52, vcc, s11, v49, s11
	v_mul_f32_e32 v53, v52, v51
	v_fma_f32 v54, -v50, v53, v52
	v_fmac_f32_e32 v53, v54, v51
	v_fma_f32 v50, -v50, v53, v52
	v_div_fmas_f32 v50, v50, v51, v53
	v_div_fixup_f32 v52, v50, v49, s11
	v_mul_f32_e32 v44, v44, v52
	v_mov_b32_e32 v53, 0x40c00000
	v_med3_f32 v51, v44, s7, v53
	v_mul_f32_e32 v44, v45, v52
	v_med3_f32 v45, v44, s7, v53
	v_mov_b32_e32 v50, 0
	v_mul_f32_e32 v36, v36, v52
	v_mul_f32_e32 v37, v37, v52
	v_cvt_scalef32_pk_fp4_f32 v50, v51, v45, 1.0
	v_med3_f32 v36, v36, s7, v53
	v_med3_f32 v37, v37, s7, v53
	v_mov_b32_e32 v51, 0
	v_mul_f32_e32 v45, v46, v52
	v_mul_f32_e32 v46, v47, v52
	v_cvt_scalef32_pk_fp4_f32 v51, v36, v37, 1.0
	v_mul_f32_e32 v36, v38, v52
	v_mul_f32_e32 v37, v39, v52
	v_med3_f32 v45, v45, s7, v53
	v_med3_f32 v46, v46, s7, v53
	v_mul_f32_e32 v40, v40, v52
	v_mul_f32_e32 v41, v41, v52
	v_med3_f32 v36, v36, s7, v53
	v_med3_f32 v37, v37, s7, v53
	v_mul_f32_e32 v32, v32, v52
	v_mul_f32_e32 v33, v33, v52
	v_cvt_scalef32_pk_fp4_f32 v50, v45, v46, 1.0 op_sel:[0,0,1,0]
	v_med3_f32 v40, v40, s7, v53
	v_med3_f32 v41, v41, s7, v53
	v_cvt_scalef32_pk_fp4_f32 v51, v36, v37, 1.0 op_sel:[0,0,1,0]
	v_med3_f32 v32, v32, s7, v53
	v_med3_f32 v33, v33, s7, v53
	v_cvt_scalef32_pk_fp4_f32 v50, v40, v41, 1.0 op_sel:[0,0,0,1]
	v_mul_f32_e32 v40, v42, v52
	v_mul_f32_e32 v41, v43, v52
	v_cvt_scalef32_pk_fp4_f32 v51, v32, v33, 1.0 op_sel:[0,0,0,1]
	v_mul_f32_e32 v32, v34, v52
	v_mul_f32_e32 v33, v35, v52
	v_med3_f32 v40, v40, s7, v53
	v_med3_f32 v41, v41, s7, v53
	v_med3_f32 v32, v32, s7, v53
	v_med3_f32 v33, v33, s7, v53
	s_brev_b32 s7, 64
	s_and_b64 s[10:11], s[8:9], exec
	s_cselect_b32 s7, s7, 0x4000000
	s_add_u32 s15, s82, s7
	s_addc_u32 s16, s83, 0
	s_ashr_i32 s7, s6, 31
	s_lshl_b64 s[10:11], s[6:7], 9
	s_add_u32 s10, s15, s10
	v_mov_b32_e32 v44, 0
	v_cvt_scalef32_pk_fp4_f32 v50, v40, v41, 1.0 op_sel:[0,0,1,1]
	v_cvt_scalef32_pk_fp4_f32 v51, v32, v33, 1.0 op_sel:[0,0,1,1]
	s_addc_u32 s11, s16, s11
	v_lshlrev_b32_e32 v32, 3, v48
	global_store_dwordx2 v32, v[50:51], s[10:11]
	s_and_saveexec_b64 s[10:11], s[0:1]
	s_cbranch_execz .LBB0_2077
	s_mov_b32 s15, 0x1d00000
	s_and_b64 s[8:9], s[8:9], exec
	s_cselect_b32 s8, s15, 0x1d00004
	s_add_u32 s8, s82, s8
	s_addc_u32 s9, s83, 0
	s_lshl_b64 s[6:7], s[6:7], 3
	s_add_u32 s6, s8, s6
	v_mul_f32_e32 v32, 0x3e124925, v49
	s_addc_u32 s7, s9, s7
	global_store_dword v44, v32, s[6:7]

; #define GAS __attribute__((address_space(1)))
; #define Q4(x) fminf(fmaxf((x) * sc, -6.f), 6.f)
; #define Q4(x) fminf(fmaxf((x) * sc, -6.f), 6.f)
; __device__ __forceinline__ void table_row_to_fp4(const f32x4 (&v)[4], int lane, bool isv, int r, unsigned char* ws) {
;     float m = 0.f;
; #pragma unroll
;     for (int j = 0; j < 4; ++j) m = fmaxf(fmaxf(m, fmaxf(fabsf(v[j].x), fabsf(v[j].y))), fmaxf(fabsf(v[j].z), fabsf(v[j].w)));
; #pragma unroll
;     for (int o = 1; o < 64; o <<= 1) m = fmaxf(m, __shfl_xor(m, o));
;     m = fmaxf(m, 1e-30f);
;     const float sc = 7.f / m;
;     unsigned w0 = 0u, w1 = 0u;
;     ...
;     w0 = __builtin_amdgcn_cvt_scalef32_pk_fp4_f32(w0, Q4(v[0].x), Q4(v[0].y), 1.0f, 0); w0 = __builtin_amdgcn_cvt_scalef32_pk_fp4_f32(w0, Q4(v[0].z), Q4(v[0].w), 1.0f, 1);
;     w0 = __builtin_amdgcn_cvt_scalef32_pk_fp4_f32(w0, Q4(v[1].x), Q4(v[1].y), 1.0f, 2); w0 = __builtin_amdgcn_cvt_scalef32_pk_fp4_f32(w0, Q4(v[1].z), Q4(v[1].w), 1.0f, 3);
;     w1 = __builtin_amdgcn_cvt_scalef32_pk_fp4_f32(w1, Q4(v[2].x), Q4(v[2].y), 1.0f, 0); w1 = __builtin_amdgcn_cvt_scalef32_pk_fp4_f32(w1, Q4(v[2].z), Q4(v[2].w), 1.0f, 1);
;     w1 = __builtin_amdgcn_cvt_scalef32_pk_fp4_f32(w1, Q4(v[3].x), Q4(v[3].y), 1.0f, 2); w1 = __builtin_amdgcn_cvt_scalef32_pk_fp4_f32(w1, Q4(v[3].z), Q4(v[3].w), 1.0f, 3);
;     ...
;     *((GAS v2u*)(ws + (isv ? WS_V8 : WS_U8) + (size_t)r * 512) + lane) = (v2u){w0, w1};
;     if (lane == 0) ((float*)(ws + (isv ? WS_DQV : WS_DQU)))[r] = m * (1.f / 7.f);
; __device__ __forceinline__ void barrier_side_convert(int k, const float* U, const float* V, unsigned char* ws) {
;     ...
;         if (j < RB && g0 + j < glim) { const int g = g0 + j, tb = g >> 14, r = NEXP * (tb >> 1) + (g & (NEXP - 1)); const GAS f32x4* src = (const GAS f32x4*)(((tb & 1) ? V : U) + (size_t)r * D) + 4 * lane;
; #pragma unroll
;             for (int q = 0; q < 4; ++q) v[jj][q] = src[q]; } }
; #pragma unroll
;     for (int jj = 0; jj < 3; ++jj) { const int j = wave - 1 + 7 * jj;
;         if (j < RB && g0 + j < glim) { const int g = g0 + j, tb = g >> 14, r = NEXP * (tb >> 1) + (g & (NEXP - 1)); table_row_to_fp4(v[jj], lane, (tb & 1) != 0, r, ws); } }
.LBB0_2078:
	s_andn2_b64 vcc, exec, s[4:5]
	s_cbranch_vccnz .LBB0_2083
	s_add_i32 s14, s14, s12
	s_cmp_gt_i32 s14, 0xffff
	s_cbranch_scc1 .LBB0_2083
	s_waitcnt vmcnt(0)
	v_max_f32_e64 v32, |v29|, |v29|
	v_max_f32_e64 v33, |v28|, |v28|
	v_max_f32_e32 v32, v33, v32
	v_max_f32_e64 v33, |v31|, |v31|
	v_max_f32_e64 v34, |v30|, |v30|
	v_max_f32_e32 v33, v34, v33
	v_max3_f32 v32, v32, 0, v33
	v_max_f32_e64 v33, |v25|, |v25|
	v_max_f32_e64 v34, |v24|, |v24|
	v_max_f32_e32 v33, v34, v33
	v_max_f32_e64 v34, |v27|, |v27|
	v_max_f32_e64 v35, |v26|, |v26|
	v_max_f32_e32 v34, v35, v34
	v_max3_f32 v32, v32, v33, v34
	v_max_f32_e64 v33, |v21|, |v21|
	v_max_f32_e64 v34, |v20|, |v20|
	v_max_f32_e32 v33, v34, v33
	v_max_f32_e64 v34, |v23|, |v23|
	v_max_f32_e64 v35, |v22|, |v22|
	v_max_f32_e32 v34, v35, v34
	v_max3_f32 v32, v32, v33, v34
	v_max_f32_e64 v33, |v17|, |v17|
	v_max_f32_e64 v34, |v16|, |v16|
	v_max_f32_e32 v33, v34, v33
	v_max_f32_e64 v34, |v19|, |v19|
	v_max_f32_e64 v35, |v18|, |v18|
	v_max_f32_e32 v34, v35, v34
	v_max3_f32 v32, v32, v33, v34
	v_mbcnt_lo_u32_b32 v33, -1, 0
	v_mbcnt_hi_u32_b32 v33, -1, v33
	v_and_b32_e32 v34, 64, v33
	v_add_u32_e32 v34, 64, v34
	v_xor_b32_e32 v35, 1, v33
	v_cmp_lt_i32_e32 vcc, v35, v34
	s_ashr_i32 s4, s14, 1
	s_and_b32 s6, s4, 0xffffc000
	v_cndmask_b32_e32 v35, v33, v35, vcc
	v_lshlrev_b32_e32 v35, 2, v35
	ds_bpermute_b32 v35, v35, v32
	s_mov_b32 s4, 0xda24260
	s_mov_b32 s8, 0x40e00000
	s_and_b32 s7, s14, 0x3fff
	s_waitcnt lgkmcnt(0)
	v_max_f32_e32 v35, v35, v35
	v_max_f32_e32 v32, v32, v35
	v_xor_b32_e32 v35, 2, v33
	v_cmp_lt_i32_e32 vcc, v35, v34
	s_nop 1
	v_cndmask_b32_e32 v35, v33, v35, vcc
	v_lshlrev_b32_e32 v35, 2, v35
	ds_bpermute_b32 v35, v35, v32
	s_waitcnt lgkmcnt(0)
	v_max_f32_e32 v35, v35, v35
	v_max_f32_e32 v32, v32, v35
	v_xor_b32_e32 v35, 4, v33
	v_cmp_lt_i32_e32 vcc, v35, v34
	s_nop 1
	v_cndmask_b32_e32 v35, v33, v35, vcc
	v_lshlrev_b32_e32 v35, 2, v35
	ds_bpermute_b32 v35, v35, v32
	s_waitcnt lgkmcnt(0)
	v_max_f32_e32 v35, v35, v35
	v_max_f32_e32 v32, v32, v35
	v_xor_b32_e32 v35, 8, v33
	v_cmp_lt_i32_e32 vcc, v35, v34
	s_nop 1
	v_cndmask_b32_e32 v35, v33, v35, vcc
	v_lshlrev_b32_e32 v35, 2, v35
	ds_bpermute_b32 v35, v35, v32
	s_waitcnt lgkmcnt(0)
	v_max_f32_e32 v35, v35, v35
	v_max_f32_e32 v32, v32, v35
	v_xor_b32_e32 v35, 16, v33
	v_cmp_lt_i32_e32 vcc, v35, v34
	s_nop 1
	v_cndmask_b32_e32 v35, v33, v35, vcc
	v_lshlrev_b32_e32 v35, 2, v35
	ds_bpermute_b32 v35, v35, v32
	s_waitcnt lgkmcnt(0)
	v_max_f32_e32 v35, v35, v35
	v_max_f32_e32 v32, v32, v35
	v_xor_b32_e32 v35, 32, v33
	v_cmp_lt_i32_e32 vcc, v35, v34
	s_nop 1
	v_cndmask_b32_e32 v33, v33, v35, vcc
	v_lshlrev_b32_e32 v33, 2, v33
	ds_bpermute_b32 v33, v33, v32
	s_waitcnt lgkmcnt(0)
	v_max3_f32 v32, v32, v33, s4
	v_div_scale_f32 v33, s[4:5], v32, v32, s8
	v_rcp_f32_e32 v34, v33
	s_mov_b32 s5, 0xc0c00000
	s_or_b32 s4, s6, s7
	s_bitcmp0_b32 s14, 14
	v_fma_f32 v35, -v33, v34, 1.0
	v_fmac_f32_e32 v34, v35, v34
	v_div_scale_f32 v35, vcc, s8, v32, s8
	v_mul_f32_e32 v36, v35, v34
	v_fma_f32 v37, -v33, v36, v35
	v_fmac_f32_e32 v36, v37, v34
	v_fma_f32 v33, -v33, v36, v35
	v_div_fmas_f32 v33, v33, v34, v36
	v_div_fixup_f32 v33, v33, v32, s8
	v_mul_f32_e32 v28, v28, v33
	v_mov_b32_e32 v36, 0x40c00000
	v_med3_f32 v35, v28, s5, v36
	v_mul_f32_e32 v28, v29, v33
	v_med3_f32 v29, v28, s5, v36
	v_mov_b32_e32 v34, 0
	v_mul_f32_e32 v20, v20, v33
	v_mul_f32_e32 v21, v21, v33
	v_cvt_scalef32_pk_fp4_f32 v34, v35, v29, 1.0
	v_med3_f32 v20, v20, s5, v36
	v_med3_f32 v21, v21, s5, v36
	v_mov_b32_e32 v35, 0
	v_mul_f32_e32 v29, v30, v33
	v_mul_f32_e32 v30, v31, v33
	v_cvt_scalef32_pk_fp4_f32 v35, v20, v21, 1.0
	v_mul_f32_e32 v20, v22, v33
	v_mul_f32_e32 v21, v23, v33
	v_med3_f32 v29, v29, s5, v36
	v_med3_f32 v30, v30, s5, v36
	v_mul_f32_e32 v24, v24, v33
	v_mul_f32_e32 v25, v25, v33
	v_med3_f32 v20, v20, s5, v36
	v_med3_f32 v21, v21, s5, v36
	v_mul_f32_e32 v16, v16, v33
	v_mul_f32_e32 v17, v17, v33
	v_cvt_scalef32_pk_fp4_f32 v34, v29, v30, 1.0 op_sel:[0,0,1,0]
	v_med3_f32 v24, v24, s5, v36
	v_med3_f32 v25, v25, s5, v36
	v_cvt_scalef32_pk_fp4_f32 v35, v20, v21, 1.0 op_sel:[0,0,1,0]
	v_med3_f32 v16, v16, s5, v36
	v_med3_f32 v17, v17, s5, v36
	s_cselect_b64 s[6:7], -1, 0
	v_cvt_scalef32_pk_fp4_f32 v34, v24, v25, 1.0 op_sel:[0,0,0,1]
	v_mul_f32_e32 v24, v26, v33
	v_mul_f32_e32 v25, v27, v33
	v_cvt_scalef32_pk_fp4_f32 v35, v16, v17, 1.0 op_sel:[0,0,0,1]
	v_mul_f32_e32 v16, v18, v33
	v_mul_f32_e32 v17, v19, v33
	v_med3_f32 v24, v24, s5, v36
	v_med3_f32 v25, v25, s5, v36
	v_med3_f32 v16, v16, s5, v36
	v_med3_f32 v17, v17, s5, v36
	s_brev_b32 s5, 64
	s_and_b64 s[8:9], s[6:7], exec
	s_cselect_b32 s5, s5, 0x4000000
	s_add_u32 s10, s82, s5
	s_addc_u32 s11, s83, 0
	s_ashr_i32 s5, s4, 31
	s_lshl_b64 s[8:9], s[4:5], 9
	s_add_u32 s8, s10, s8
	v_mov_b32_e32 v28, 0
	v_cvt_scalef32_pk_fp4_f32 v34, v24, v25, 1.0 op_sel:[0,0,1,1]
	v_cvt_scalef32_pk_fp4_f32 v35, v16, v17, 1.0 op_sel:[0,0,1,1]
	s_addc_u32 s9, s11, s9
	v_lshlrev_b32_e32 v16, 3, v48
	global_store_dwordx2 v16, v[34:35], s[8:9]
	s_and_saveexec_b64 s[8:9], s[0:1]
	s_cbranch_execz .LBB0_2082
	s_mov_b32 s10, 0x1d00000
	s_and_b64 s[6:7], s[6:7], exec
	s_cselect_b32 s6, s10, 0x1d00004
	s_add_u32 s6, s82, s6
	s_addc_u32 s7, s83, 0
	s_lshl_b64 s[4:5], s[4:5], 3
	s_add_u32 s4, s6, s4
	v_mul_f32_e32 v16, 0x3e124925, v32
	s_addc_u32 s5, s7, s5
	global_store_dword v28, v16, s[4:5]

; #define GAS __attribute__((address_space(1)))
; #define Q4(x) fminf(fmaxf((x) * sc, -6.f), 6.f)
; #define Q4(x) fminf(fmaxf((x) * sc, -6.f), 6.f)
; __device__ __forceinline__ void table_row_to_fp4(const f32x4 (&v)[4], int lane, bool isv, int r, unsigned char* ws) {
;     float m = 0.f;
; #pragma unroll
;     for (int j = 0; j < 4; ++j) m = fmaxf(fmaxf(m, fmaxf(fabsf(v[j].x), fabsf(v[j].y))), fmaxf(fabsf(v[j].z), fabsf(v[j].w)));
; #pragma unroll
;     for (int o = 1; o < 64; o <<= 1) m = fmaxf(m, __shfl_xor(m, o));
;     m = fmaxf(m, 1e-30f);
;     const float sc = 7.f / m;
;     unsigned w0 = 0u, w1 = 0u;
;     ...
;     w0 = __builtin_amdgcn_cvt_scalef32_pk_fp4_f32(w0, Q4(v[0].x), Q4(v[0].y), 1.0f, 0); w0 = __builtin_amdgcn_cvt_scalef32_pk_fp4_f32(w0, Q4(v[0].z), Q4(v[0].w), 1.0f, 1);
;     w0 = __builtin_amdgcn_cvt_scalef32_pk_fp4_f32(w0, Q4(v[1].x), Q4(v[1].y), 1.0f, 2); w0 = __builtin_amdgcn_cvt_scalef32_pk_fp4_f32(w0, Q4(v[1].z), Q4(v[1].w), 1.0f, 3);
;     w1 = __builtin_amdgcn_cvt_scalef32_pk_fp4_f32(w1, Q4(v[2].x), Q4(v[2].y), 1.0f, 0); w1 = __builtin_amdgcn_cvt_scalef32_pk_fp4_f32(w1, Q4(v[2].z), Q4(v[2].w), 1.0f, 1);
;     w1 = __builtin_amdgcn_cvt_scalef32_pk_fp4_f32(w1, Q4(v[3].x), Q4(v[3].y), 1.0f, 2); w1 = __builtin_amdgcn_cvt_scalef32_pk_fp4_f32(w1, Q4(v[3].z), Q4(v[3].w), 1.0f, 3);
;     ...
;     *((GAS v2u*)(ws + (isv ? WS_V8 : WS_U8) + (size_t)r * 512) + lane) = (v2u){w0, w1};
;     if (lane == 0) ((float*)(ws + (isv ? WS_DQV : WS_DQU)))[r] = m * (1.f / 7.f);
; __device__ __forceinline__ void barrier_side_convert(int k, const float* U, const float* V, unsigned char* ws) {
;     ...
;         if (j < RB && g0 + j < glim) { const int g = g0 + j, tb = g >> 14, r = NEXP * (tb >> 1) + (g & (NEXP - 1)); const GAS f32x4* src = (const GAS f32x4*)(((tb & 1) ? V : U) + (size_t)r * D) + 4 * lane;
; #pragma unroll
;             for (int q = 0; q < 4; ++q) v[jj][q] = src[q]; } }
; #pragma unroll
;     for (int jj = 0; jj < 3; ++jj) { const int j = wave - 1 + 7 * jj;
;         if (j < RB && g0 + j < glim) { const int g = g0 + j, tb = g >> 14, r = NEXP * (tb >> 1) + (g & (NEXP - 1)); table_row_to_fp4(v[jj], lane, (tb & 1) != 0, r, ws); } }
.LBB0_2083:
	s_andn2_b64 vcc, exec, s[2:3]
	s_cbranch_vccnz .LBB0_2088
	s_add_i32 s13, s13, s12
	s_cmp_gt_i32 s13, 0xffff
	s_cbranch_scc1 .LBB0_2088
	s_waitcnt vmcnt(0)
	v_max_f32_e64 v16, |v13|, |v13|
	v_max_f32_e64 v17, |v12|, |v12|
	v_max_f32_e32 v16, v17, v16
	v_max_f32_e64 v17, |v15|, |v15|
	v_max_f32_e64 v18, |v14|, |v14|
	v_max_f32_e32 v17, v18, v17
	v_max3_f32 v16, v16, 0, v17
	v_max_f32_e64 v17, |v9|, |v9|
	v_max_f32_e64 v18, |v8|, |v8|
	v_max_f32_e32 v17, v18, v17
	v_max_f32_e64 v18, |v11|, |v11|
	v_max_f32_e64 v19, |v10|, |v10|
	v_max_f32_e32 v18, v19, v18
	v_max3_f32 v16, v16, v17, v18
	v_max_f32_e64 v17, |v5|, |v5|
	v_max_f32_e64 v18, |v4|, |v4|
	v_max_f32_e32 v17, v18, v17
	v_max_f32_e64 v18, |v7|, |v7|
	v_max_f32_e64 v19, |v6|, |v6|
	v_max_f32_e32 v18, v19, v18
	v_max3_f32 v16, v16, v17, v18
	v_max_f32_e64 v17, |v1|, |v1|
	v_max_f32_e64 v18, |v0|, |v0|
	v_max_f32_e32 v17, v18, v17
	v_max_f32_e64 v18, |v3|, |v3|
	v_max_f32_e64 v19, |v2|, |v2|
	v_max_f32_e32 v18, v19, v18
	v_max3_f32 v16, v16, v17, v18
	v_mbcnt_lo_u32_b32 v17, -1, 0
	v_mbcnt_hi_u32_b32 v17, -1, v17
	v_and_b32_e32 v18, 64, v17
	v_add_u32_e32 v18, 64, v18
	v_xor_b32_e32 v19, 1, v17
	v_cmp_lt_i32_e32 vcc, v19, v18
	s_ashr_i32 s2, s13, 1
	s_and_b32 s4, s2, 0xffffc000
	v_cndmask_b32_e32 v19, v17, v19, vcc
	v_lshlrev_b32_e32 v19, 2, v19
	ds_bpermute_b32 v19, v19, v16
	s_mov_b32 s2, 0xda24260
	s_mov_b32 s6, 0x40e00000
	s_and_b32 s5, s13, 0x3fff
	s_waitcnt lgkmcnt(0)
	v_max_f32_e32 v19, v19, v19
	v_max_f32_e32 v16, v16, v19
	v_xor_b32_e32 v19, 2, v17
	v_cmp_lt_i32_e32 vcc, v19, v18
	s_nop 1
	v_cndmask_b32_e32 v19, v17, v19, vcc
	v_lshlrev_b32_e32 v19, 2, v19
	ds_bpermute_b32 v19, v19, v16
	s_waitcnt lgkmcnt(0)
	v_max_f32_e32 v19, v19, v19
	v_max_f32_e32 v16, v16, v19
	v_xor_b32_e32 v19, 4, v17
	v_cmp_lt_i32_e32 vcc, v19, v18
	s_nop 1
	v_cndmask_b32_e32 v19, v17, v19, vcc
	v_lshlrev_b32_e32 v19, 2, v19
	ds_bpermute_b32 v19, v19, v16
	s_waitcnt lgkmcnt(0)
	v_max_f32_e32 v19, v19, v19
	v_max_f32_e32 v16, v16, v19
	v_xor_b32_e32 v19, 8, v17
	v_cmp_lt_i32_e32 vcc, v19, v18
	s_nop 1
	v_cndmask_b32_e32 v19, v17, v19, vcc
	v_lshlrev_b32_e32 v19, 2, v19
	ds_bpermute_b32 v19, v19, v16
	s_waitcnt lgkmcnt(0)
	v_max_f32_e32 v19, v19, v19
	v_max_f32_e32 v16, v16, v19
	v_xor_b32_e32 v19, 16, v17
	v_cmp_lt_i32_e32 vcc, v19, v18
	s_nop 1
	v_cndmask_b32_e32 v19, v17, v19, vcc
	v_lshlrev_b32_e32 v19, 2, v19
	ds_bpermute_b32 v19, v19, v16
	s_waitcnt lgkmcnt(0)
	v_max_f32_e32 v19, v19, v19
	v_max_f32_e32 v16, v16, v19
	v_xor_b32_e32 v19, 32, v17
	v_cmp_lt_i32_e32 vcc, v19, v18
	s_nop 1
	v_cndmask_b32_e32 v17, v17, v19, vcc
	v_lshlrev_b32_e32 v17, 2, v17
	ds_bpermute_b32 v17, v17, v16
	s_waitcnt lgkmcnt(0)
	v_max3_f32 v16, v16, v17, s2
	v_div_scale_f32 v17, s[2:3], v16, v16, s6
	v_rcp_f32_e32 v18, v17
	s_mov_b32 s3, 0xc0c00000
	s_or_b32 s2, s4, s5
	s_bitcmp0_b32 s13, 14
	v_fma_f32 v19, -v17, v18, 1.0
	v_fmac_f32_e32 v18, v19, v18
	v_div_scale_f32 v19, vcc, s6, v16, s6
	v_mul_f32_e32 v20, v19, v18
	v_fma_f32 v21, -v17, v20, v19
	v_fmac_f32_e32 v20, v21, v18
	v_fma_f32 v17, -v17, v20, v19
	v_div_fmas_f32 v17, v17, v18, v20
	v_div_fixup_f32 v17, v17, v16, s6
	v_mul_f32_e32 v12, v12, v17
	v_mov_b32_e32 v20, 0x40c00000
	v_med3_f32 v19, v12, s3, v20
	v_mul_f32_e32 v12, v13, v17
	v_med3_f32 v13, v12, s3, v20
	v_mov_b32_e32 v18, 0
	v_mul_f32_e32 v4, v4, v17
	v_mul_f32_e32 v5, v5, v17
	v_cvt_scalef32_pk_fp4_f32 v18, v19, v13, 1.0
	v_med3_f32 v4, v4, s3, v20
	v_med3_f32 v5, v5, s3, v20
	v_mov_b32_e32 v19, 0
	v_mul_f32_e32 v13, v14, v17
	v_mul_f32_e32 v14, v15, v17
	v_cvt_scalef32_pk_fp4_f32 v19, v4, v5, 1.0
	v_mul_f32_e32 v4, v6, v17
	v_mul_f32_e32 v5, v7, v17
	v_med3_f32 v13, v13, s3, v20
	v_med3_f32 v14, v14, s3, v20
	v_mul_f32_e32 v8, v8, v17
	v_mul_f32_e32 v9, v9, v17
	v_med3_f32 v4, v4, s3, v20
	v_med3_f32 v5, v5, s3, v20
	v_mul_f32_e32 v0, v0, v17
	v_mul_f32_e32 v1, v1, v17
	v_cvt_scalef32_pk_fp4_f32 v18, v13, v14, 1.0 op_sel:[0,0,1,0]
	v_med3_f32 v8, v8, s3, v20
	v_med3_f32 v9, v9, s3, v20
	v_cvt_scalef32_pk_fp4_f32 v19, v4, v5, 1.0 op_sel:[0,0,1,0]
	v_med3_f32 v0, v0, s3, v20
	v_med3_f32 v1, v1, s3, v20
	s_cselect_b64 s[4:5], -1, 0
	v_cvt_scalef32_pk_fp4_f32 v18, v8, v9, 1.0 op_sel:[0,0,0,1]
	v_mul_f32_e32 v8, v10, v17
	v_mul_f32_e32 v9, v11, v17
	v_cvt_scalef32_pk_fp4_f32 v19, v0, v1, 1.0 op_sel:[0,0,0,1]
	v_mul_f32_e32 v0, v2, v17
	v_mul_f32_e32 v1, v3, v17
	v_med3_f32 v8, v8, s3, v20
	v_med3_f32 v9, v9, s3, v20
	v_med3_f32 v0, v0, s3, v20
	v_med3_f32 v1, v1, s3, v20
	s_brev_b32 s3, 64
	s_and_b64 s[6:7], s[4:5], exec
	s_cselect_b32 s3, s3, 0x4000000
	s_add_u32 s8, s82, s3
	s_addc_u32 s9, s83, 0
	s_ashr_i32 s3, s2, 31
	s_lshl_b64 s[6:7], s[2:3], 9
	s_add_u32 s6, s8, s6
	v_mov_b32_e32 v12, 0
	v_cvt_scalef32_pk_fp4_f32 v18, v8, v9, 1.0 op_sel:[0,0,1,1]
	v_cvt_scalef32_pk_fp4_f32 v19, v0, v1, 1.0 op_sel:[0,0,1,1]
	s_addc_u32 s7, s9, s7
	v_lshlrev_b32_e32 v0, 3, v48
	global_store_dwordx2 v0, v[18:19], s[6:7]
	s_and_saveexec_b64 s[6:7], s[0:1]
	s_cbranch_execz .LBB0_2087
	s_mov_b32 s8, 0x1d00000
	s_and_b64 s[0:1], s[4:5], exec
	s_cselect_b32 s0, s8, 0x1d00004
	s_add_u32 s4, s82, s0
	s_addc_u32 s5, s83, 0
	s_lshl_b64 s[0:1], s[2:3], 3
	s_add_u32 s0, s4, s0
	v_mul_f32_e32 v0, 0x3e124925, v16
	s_addc_u32 s1, s5, s1
	global_store_dword v12, v0, s[0:1]
